# MT2 sliding-window attention latent tile loop rewritten by hand (interior tiles unmasked, edge tiles one-sided mask, sum-based pow2 rescale)
# speedup vs baseline: 1.0367x; 1.0031x over previous
.LBB0_1069:
	v_lshlrev_b32_e32 v11, 3, v16
	v_add_u32_e32 v18, s17, v161
	v_mov_b64_e32 v[16:17], s[2:3]
	v_mad_i64_i32 v[16:17], s[6:7], v18, s33, v[16:17]
	v_add_u32_e32 v20, s17, v171
	v_mov_b64_e32 v[18:19], s[4:5]
	v_lshl_add_u64 v[16:17], v[8:9], 1, v[16:17]
	v_mad_i64_i32 v[18:19], s[6:7], v20, s33, v[18:19]
	v_lshlrev_b32_e32 v184, 1, v11
	v_lshl_add_u64 v[18:19], v[18:19], 0, v[184:185]
	global_load_dwordx4 v[112:115], v[16:17], off
	global_load_dwordx4 v[116:119], v[18:19], off
	v_mul_lo_u32 v11, v161, s81
	v_add_u32_e32 v11, 0, v11
	v_lshlrev_b32_e32 v15, 4, v15
	v_add_u32_e32 v172, v11, v15
	s_waitcnt vmcnt(3)
	ds_write_b128 v172, v[4:7]
	v_mul_lo_u32 v4, v171, s80
	v_add_u32_e32 v4, 0, v4
	v_add_u32_e32 v173, v4, v10
	s_waitcnt vmcnt(2)
	ds_write_b128 v173, v[0:3] offset:26624
	s_waitcnt lgkmcnt(0)
	s_barrier
	s_cmp_lt_i32 s20, -11
	s_cbranch_scc1 .LBB0_1059
	v_lshl_add_u64 v[164:165], v[8:9], 1, s[2:3]
	s_lshl_b32 s2, s21, 6
	v_lshlrev_b32_e32 v0, 2, v169
	v_lshrrev_b32_e32 v1, 2, v13
	s_add_i32 s21, s2, 0xffffff80
	v_readlane_b32 s2, v255, 7
	v_and_or_b32 v1, v1, 3, v0
	v_and_b32_e32 v2, 16, v13
	v_lshlrev_b32_e32 v3, 2, v12
	v_sub_u32_e32 v177, v0, v14
	v_add_u32_e32 v0, s2, v0
	s_lshl_b32 s16, s16, 8
	v_and_or_b32 v2, v3, 12, v2
	v_sub_u32_e32 v0, v0, v12
	v_mov_b32_e32 v163, 0
	v_lshl_add_u64 v[166:167], s[4:5], 0, v[184:185]
	s_add_i32 s6, s20, 12
	s_add_i32 s7, s20, 11
	s_add_i32 s16, s16, 0x8000
	s_add_i32 s17, s18, 0xffffff80
	s_addk_i32 s18, 0x9f
	v_mad_u32_u24 v174, v12, s81, 0
	s_mov_b32 s19, 3
	v_lshlrev_b32_e32 v175, 1, v2
	v_mad_u32_u24 v176, v1, s80, 0
	s_sub_i32 s20, -8, s20
	v_subrev_u32_e32 v178, s24, v0
	v_mov_b32_e32 v168, 0xf149f2ca
	v_mov_b32_e32 v16, 0
	v_mov_b32_e32 v17, v163
	v_mov_b32_e32 v18, v163
	v_mov_b32_e32 v19, v163
	v_mov_b32_e32 v20, v163
	v_mov_b32_e32 v21, v163
	v_mov_b32_e32 v22, v163
	v_mov_b32_e32 v23, v163
	v_mov_b32_e32 v24, v163
	v_mov_b32_e32 v25, v163
	v_mov_b32_e32 v26, v163
	v_mov_b32_e32 v27, v163
	v_mov_b32_e32 v28, v163
	v_mov_b32_e32 v29, v163
	v_mov_b32_e32 v30, v163
	v_mov_b32_e32 v31, v163
	v_mov_b32_e32 v0, v163
	v_mov_b32_e32 v1, v163
	v_mov_b32_e32 v2, v163
	v_mov_b32_e32 v3, v163
	v_mov_b32_e32 v4, v163
	v_mov_b32_e32 v5, v163
	v_mov_b32_e32 v6, v163
	v_mov_b32_e32 v7, v163
	v_mov_b32_e32 v8, v163
	v_mov_b32_e32 v9, v163
	v_mov_b32_e32 v10, v163
	v_mov_b32_e32 v11, v163
	v_mov_b32_e32 v12, v163
	v_mov_b32_e32 v13, v163
	v_mov_b32_e32 v14, v163
	v_mov_b32_e32 v15, v163
	v_mov_b32_e32 v168, 0
	v_mov_b32_e32 v218, 0
	v_mov_b32_e32 v219, 0
	v_mov_b32_e32 v220, 0
	v_mov_b32_e32 v221, 0
	v_mov_b32_e32 v222, 0
	v_mov_b32_e32 v223, 0
	v_mov_b32_e32 v224, 0
	v_mov_b32_e32 v225, 0
	v_mov_b32_e32 v226, 0
	v_mov_b32_e32 v227, 0
	v_mov_b32_e32 v228, 0
	v_mov_b32_e32 v229, 0
	v_mov_b32_e32 v230, 0
	v_mov_b32_e32 v231, 0
	v_mov_b32_e32 v232, 0
	v_mov_b32_e32 v233, 0
.LBB0_1072:
	s_add_i32 s24, s19, -1
	s_min_i32 s24, s24, s7
	s_cmp_lt_i32 s24, s14
	s_cselect_b32 s25, s15, s20
	s_cselect_b32 s26, s13, s16
	s_add_i32 s25, s25, s24
	s_lshl_b32 s25, s25, 6
	s_add_i32 s26, s26, s25
	v_add_u32_e32 v236, s26, v161
	v_mad_i64_i32 v[236:237], s[98:99], v236, s33, v[164:165]
	global_load_dwordx4 v[120:123], v[236:237], off
	v_add_u32_e32 v236, s26, v171
	v_mad_i64_i32 v[236:237], s[98:99], v236, s33, v[166:167]
	global_load_dwordx4 v[124:127], v[236:237], off
	s_add_i32 s24, s19, -3
	s_cmp_ge_i32 s24, s14
	s_cbranch_scc1 .Lm2_fullA
	s_mov_b32 s27, s21
	s_add_i32 s25, s27, 63
	s_cmp_lt_i32 s25, s17
	s_cbranch_scc1 .Lm2_doneA
	s_cmp_gt_i32 s27, s18
	s_cbranch_scc1 .Lm2_doneA
	s_add_i32 s25, s17, 31
	s_cmp_lt_i32 s27, s25
	s_cbranch_scc1 .Lm2_lowA
	s_add_i32 s25, s17, 0xc1
	s_cmp_gt_i32 s27, s25
	s_cbranch_scc1 .Lm2_highA
.Lm2_fullA:
	v_add_u32_e32 v236, v174, v162
	ds_read_b128 v[128:131], v236
	ds_read_b128 v[144:147], v236 offset:6656
	ds_read_b128 v[132:135], v236 offset:32
	ds_read_b128 v[148:151], v236 offset:6688
	ds_read_b128 v[136:139], v236 offset:64
	ds_read_b128 v[152:155], v236 offset:6720
	ds_read_b128 v[140:143], v236 offset:96
	ds_read_b128 v[156:159], v236 offset:6752
	v_add_u32_e32 v237, v176, v175
	s_waitcnt lgkmcnt(7)
	v_mfma_f32_32x32x16_bf16 v[32:47], v[128:131], v[96:99], v[218:233]
	s_waitcnt lgkmcnt(6)
	v_mfma_f32_32x32x16_bf16 v[48:63], v[144:147], v[96:99], v[218:233]
	s_waitcnt lgkmcnt(5)
	v_mfma_f32_32x32x16_bf16 v[32:47], v[132:135], v[100:103], v[32:47]
	s_waitcnt lgkmcnt(4)
	v_mfma_f32_32x32x16_bf16 v[48:63], v[148:151], v[100:103], v[48:63]
	s_waitcnt lgkmcnt(3)
	v_mfma_f32_32x32x16_bf16 v[32:47], v[136:139], v[104:107], v[32:47]
	s_waitcnt lgkmcnt(2)
	v_mfma_f32_32x32x16_bf16 v[48:63], v[152:155], v[104:107], v[48:63]
	s_waitcnt lgkmcnt(1)
	v_mfma_f32_32x32x16_bf16 v[32:47], v[140:143], v[108:111], v[32:47]
	s_waitcnt lgkmcnt(0)
	v_mfma_f32_32x32x16_bf16 v[48:63], v[156:159], v[108:111], v[48:63]
	ds_read_b64_tr_b16 v[186:187], v237 offset:26624
	ds_read_b64_tr_b16 v[188:189], v237 offset:28160
	ds_read_b64_tr_b16 v[190:191], v237 offset:26688
	ds_read_b64_tr_b16 v[192:193], v237 offset:28224
	ds_read_b64_tr_b16 v[194:195], v237 offset:29696
	ds_read_b64_tr_b16 v[196:197], v237 offset:31232
	ds_read_b64_tr_b16 v[198:199], v237 offset:29760
	ds_read_b64_tr_b16 v[200:201], v237 offset:31296
	ds_read_b64_tr_b16 v[202:203], v237 offset:32768
	ds_read_b64_tr_b16 v[204:205], v237 offset:34304
	ds_read_b64_tr_b16 v[206:207], v237 offset:32832
	ds_read_b64_tr_b16 v[208:209], v237 offset:34368
	ds_read_b64_tr_b16 v[210:211], v237 offset:35840
	ds_read_b64_tr_b16 v[212:213], v237 offset:37376
	ds_read_b64_tr_b16 v[214:215], v237 offset:35904
	ds_read_b64_tr_b16 v[216:217], v237 offset:37440
	v_mul_f32_e32 v32, 0x3e38aa3b, v32
	v_mul_f32_e32 v33, 0x3e38aa3b, v33
	v_mul_f32_e32 v34, 0x3e38aa3b, v34
	v_mul_f32_e32 v35, 0x3e38aa3b, v35
	v_mul_f32_e32 v36, 0x3e38aa3b, v36
	v_mul_f32_e32 v37, 0x3e38aa3b, v37
	v_mul_f32_e32 v38, 0x3e38aa3b, v38
	v_mul_f32_e32 v39, 0x3e38aa3b, v39
	v_exp_f32_e32 v32, v32
	v_exp_f32_e32 v33, v33
	v_exp_f32_e32 v34, v34
	v_exp_f32_e32 v35, v35
	v_exp_f32_e32 v36, v36
	v_exp_f32_e32 v37, v37
	v_exp_f32_e32 v38, v38
	v_exp_f32_e32 v39, v39
	v_add_f32_e32 v234, v32, v34
	v_add_f32_e32 v235, v33, v35
	v_add_f32_e32 v234, v234, v36
	v_add_f32_e32 v235, v235, v37
	v_add_f32_e32 v234, v234, v38
	v_add_f32_e32 v235, v235, v39
	v_cvt_pk_bf16_f32 v32, v32, v33
	v_cvt_pk_bf16_f32 v33, v34, v35
	v_cvt_pk_bf16_f32 v34, v36, v37
	v_cvt_pk_bf16_f32 v35, v38, v39
	v_mul_f32_e32 v40, 0x3e38aa3b, v40
	v_mul_f32_e32 v41, 0x3e38aa3b, v41
	s_waitcnt lgkmcnt(14)
	v_mfma_f32_32x32x16_bf16 v[16:31], v[186:189], v[32:35], v[16:31]
	v_mul_f32_e32 v42, 0x3e38aa3b, v42
	v_mul_f32_e32 v43, 0x3e38aa3b, v43
	v_mul_f32_e32 v44, 0x3e38aa3b, v44
	v_mul_f32_e32 v45, 0x3e38aa3b, v45
	v_mul_f32_e32 v46, 0x3e38aa3b, v46
	v_mul_f32_e32 v47, 0x3e38aa3b, v47
	s_waitcnt lgkmcnt(12)
	v_mfma_f32_32x32x16_bf16 v[0:15], v[190:193], v[32:35], v[0:15]
	v_exp_f32_e32 v40, v40
	v_exp_f32_e32 v41, v41
	v_exp_f32_e32 v42, v42
	v_exp_f32_e32 v43, v43
	v_exp_f32_e32 v44, v44
	v_exp_f32_e32 v45, v45
	v_exp_f32_e32 v46, v46
	v_exp_f32_e32 v47, v47
	v_add_f32_e32 v234, v234, v40
	v_add_f32_e32 v235, v235, v41
	v_add_f32_e32 v234, v234, v42
	v_add_f32_e32 v235, v235, v43
	v_add_f32_e32 v234, v234, v44
	v_add_f32_e32 v235, v235, v45
	v_add_f32_e32 v234, v234, v46
	v_add_f32_e32 v235, v235, v47
	v_cvt_pk_bf16_f32 v40, v40, v41
	v_cvt_pk_bf16_f32 v41, v42, v43
	v_cvt_pk_bf16_f32 v42, v44, v45
	v_cvt_pk_bf16_f32 v43, v46, v47
	v_mul_f32_e32 v48, 0x3e38aa3b, v48
	v_mul_f32_e32 v49, 0x3e38aa3b, v49
	s_waitcnt lgkmcnt(10)
	v_mfma_f32_32x32x16_bf16 v[16:31], v[194:197], v[40:43], v[16:31]
	v_mul_f32_e32 v50, 0x3e38aa3b, v50
	v_mul_f32_e32 v51, 0x3e38aa3b, v51
	v_mul_f32_e32 v52, 0x3e38aa3b, v52
	v_mul_f32_e32 v53, 0x3e38aa3b, v53
	v_mul_f32_e32 v54, 0x3e38aa3b, v54
	v_mul_f32_e32 v55, 0x3e38aa3b, v55
	s_waitcnt lgkmcnt(8)
	v_mfma_f32_32x32x16_bf16 v[0:15], v[198:201], v[40:43], v[0:15]
	v_exp_f32_e32 v48, v48
	v_exp_f32_e32 v49, v49
	v_exp_f32_e32 v50, v50
	v_exp_f32_e32 v51, v51
	v_exp_f32_e32 v52, v52
	v_exp_f32_e32 v53, v53
	v_exp_f32_e32 v54, v54
	v_exp_f32_e32 v55, v55
	v_add_f32_e32 v234, v234, v48
	v_add_f32_e32 v235, v235, v49
	v_add_f32_e32 v234, v234, v50
	v_add_f32_e32 v235, v235, v51
	v_add_f32_e32 v234, v234, v52
	v_add_f32_e32 v235, v235, v53
	v_add_f32_e32 v234, v234, v54
	v_add_f32_e32 v235, v235, v55
	v_cvt_pk_bf16_f32 v48, v48, v49
	v_cvt_pk_bf16_f32 v49, v50, v51
	v_cvt_pk_bf16_f32 v50, v52, v53
	v_cvt_pk_bf16_f32 v51, v54, v55
	v_mul_f32_e32 v56, 0x3e38aa3b, v56
	v_mul_f32_e32 v57, 0x3e38aa3b, v57
	s_waitcnt lgkmcnt(6)
	v_mfma_f32_32x32x16_bf16 v[16:31], v[202:205], v[48:51], v[16:31]
	v_mul_f32_e32 v58, 0x3e38aa3b, v58
	v_mul_f32_e32 v59, 0x3e38aa3b, v59
	v_mul_f32_e32 v60, 0x3e38aa3b, v60
	v_mul_f32_e32 v61, 0x3e38aa3b, v61
	v_mul_f32_e32 v62, 0x3e38aa3b, v62
	v_mul_f32_e32 v63, 0x3e38aa3b, v63
	s_waitcnt lgkmcnt(4)
	v_mfma_f32_32x32x16_bf16 v[0:15], v[206:209], v[48:51], v[0:15]
	v_exp_f32_e32 v56, v56
	v_exp_f32_e32 v57, v57
	v_exp_f32_e32 v58, v58
	v_exp_f32_e32 v59, v59
	v_exp_f32_e32 v60, v60
	v_exp_f32_e32 v61, v61
	v_exp_f32_e32 v62, v62
	v_exp_f32_e32 v63, v63
	v_add_f32_e32 v234, v234, v56
	v_add_f32_e32 v235, v235, v57
	v_add_f32_e32 v234, v234, v58
	v_add_f32_e32 v235, v235, v59
	v_add_f32_e32 v234, v234, v60
	v_add_f32_e32 v235, v235, v61
	v_add_f32_e32 v234, v234, v62
	v_add_f32_e32 v235, v235, v63
	v_cvt_pk_bf16_f32 v56, v56, v57
	v_cvt_pk_bf16_f32 v57, v58, v59
	v_cvt_pk_bf16_f32 v58, v60, v61
	v_cvt_pk_bf16_f32 v59, v62, v63
	s_nop 1
	s_waitcnt lgkmcnt(2)
	v_mfma_f32_32x32x16_bf16 v[16:31], v[210:213], v[56:59], v[16:31]
	s_waitcnt lgkmcnt(0)
	v_mfma_f32_32x32x16_bf16 v[0:15], v[214:217], v[56:59], v[0:15]
	v_add_f32_e32 v234, v234, v235
	v_add_f32_e32 v163, v163, v234
	v_cmp_lt_f32_e32 vcc, 0x43000000, v234
	s_cbranch_vccz .Lm2_nr_fA
	s_nop 15
	v_mov_b32_e32 v235, v234
	s_nop 1
	v_permlane32_swap_b32_e32 v234, v235
	v_add_f32_e32 v178, v234, v235
	v_cmp_lt_f32_e32 vcc, 0x43800000, v178
	v_frexp_exp_i32_f32_e32 v179, v178
	s_nop 1
	v_cndmask_b32_e32 v179, 0, v179, vcc
	v_cvt_f32_i32_e32 v180, v179
	v_sub_u32_e32 v179, 0, v179
	v_ldexp_f32 v178, 1.0, v179
	v_add_f32_e32 v168, v168, v180
	v_mul_f32_e32 v163, v163, v178
	v_mul_f32_e32 v0, v0, v178
	v_mul_f32_e32 v1, v1, v178
	v_mul_f32_e32 v2, v2, v178
	v_mul_f32_e32 v3, v3, v178
	v_mul_f32_e32 v4, v4, v178
	v_mul_f32_e32 v5, v5, v178
	v_mul_f32_e32 v6, v6, v178
	v_mul_f32_e32 v7, v7, v178
	v_mul_f32_e32 v8, v8, v178
	v_mul_f32_e32 v9, v9, v178
	v_mul_f32_e32 v10, v10, v178
	v_mul_f32_e32 v11, v11, v178
	v_mul_f32_e32 v12, v12, v178
	v_mul_f32_e32 v13, v13, v178
	v_mul_f32_e32 v14, v14, v178
	v_mul_f32_e32 v15, v15, v178
	v_mul_f32_e32 v16, v16, v178
	v_mul_f32_e32 v17, v17, v178
	v_mul_f32_e32 v18, v18, v178
	v_mul_f32_e32 v19, v19, v178
	v_mul_f32_e32 v20, v20, v178
	v_mul_f32_e32 v21, v21, v178
	v_mul_f32_e32 v22, v22, v178
	v_mul_f32_e32 v23, v23, v178
	v_mul_f32_e32 v24, v24, v178
	v_mul_f32_e32 v25, v25, v178
	v_mul_f32_e32 v26, v26, v178
	v_mul_f32_e32 v27, v27, v178
	v_mul_f32_e32 v28, v28, v178
	v_mul_f32_e32 v29, v29, v178
	v_mul_f32_e32 v30, v30, v178
	v_mul_f32_e32 v31, v31, v178
	v_mul_f32_e32 v218, 0xc0b17218, v168
	v_mov_b32_e32 v219, v218
	v_mov_b32_e32 v220, v218
	v_mov_b32_e32 v221, v218
	v_mov_b32_e32 v222, v218
	v_mov_b32_e32 v223, v218
	v_mov_b32_e32 v224, v218
	v_mov_b32_e32 v225, v218
	v_mov_b32_e32 v226, v218
	v_mov_b32_e32 v227, v218
	v_mov_b32_e32 v228, v218
	v_mov_b32_e32 v229, v218
	v_mov_b32_e32 v230, v218
	v_mov_b32_e32 v231, v218
	v_mov_b32_e32 v232, v218
	v_mov_b32_e32 v233, v218

.Lm2_lowA:
	v_add_u32_e32 v236, v174, v162
	ds_read_b128 v[128:131], v236
	ds_read_b128 v[144:147], v236 offset:6656
	ds_read_b128 v[132:135], v236 offset:32
	ds_read_b128 v[148:151], v236 offset:6688
	ds_read_b128 v[136:139], v236 offset:64
	ds_read_b128 v[152:155], v236 offset:6720
	ds_read_b128 v[140:143], v236 offset:96
	ds_read_b128 v[156:159], v236 offset:6752
	v_add_u32_e32 v237, v176, v175
	s_add_i32 s27, s27, 0x80
	v_add_u32_e32 v178, s27, v177
	v_sub_u32_e32 v178, 0, v178
	s_waitcnt lgkmcnt(7)
	v_mfma_f32_32x32x16_bf16 v[32:47], v[128:131], v[96:99], v[218:233]
	s_waitcnt lgkmcnt(6)
	v_mfma_f32_32x32x16_bf16 v[48:63], v[144:147], v[96:99], v[218:233]
	s_waitcnt lgkmcnt(5)
	v_mfma_f32_32x32x16_bf16 v[32:47], v[132:135], v[100:103], v[32:47]
	s_waitcnt lgkmcnt(4)
	v_mfma_f32_32x32x16_bf16 v[48:63], v[148:151], v[100:103], v[48:63]
	s_waitcnt lgkmcnt(3)
	v_mfma_f32_32x32x16_bf16 v[32:47], v[136:139], v[104:107], v[32:47]
	s_waitcnt lgkmcnt(2)
	v_mfma_f32_32x32x16_bf16 v[48:63], v[152:155], v[104:107], v[48:63]
	s_waitcnt lgkmcnt(1)
	v_mfma_f32_32x32x16_bf16 v[32:47], v[140:143], v[108:111], v[32:47]
	s_waitcnt lgkmcnt(0)
	v_mfma_f32_32x32x16_bf16 v[48:63], v[156:159], v[108:111], v[48:63]
	ds_read_b64_tr_b16 v[186:187], v237 offset:26624
	ds_read_b64_tr_b16 v[188:189], v237 offset:28160
	ds_read_b64_tr_b16 v[190:191], v237 offset:26688
	ds_read_b64_tr_b16 v[192:193], v237 offset:28224
	ds_read_b64_tr_b16 v[194:195], v237 offset:29696
	ds_read_b64_tr_b16 v[196:197], v237 offset:31232
	ds_read_b64_tr_b16 v[198:199], v237 offset:29760
	ds_read_b64_tr_b16 v[200:201], v237 offset:31296
	ds_read_b64_tr_b16 v[202:203], v237 offset:32768
	ds_read_b64_tr_b16 v[204:205], v237 offset:34304
	ds_read_b64_tr_b16 v[206:207], v237 offset:32832
	ds_read_b64_tr_b16 v[208:209], v237 offset:34368
	ds_read_b64_tr_b16 v[210:211], v237 offset:35840
	ds_read_b64_tr_b16 v[212:213], v237 offset:37376
	ds_read_b64_tr_b16 v[214:215], v237 offset:35904
	ds_read_b64_tr_b16 v[216:217], v237 offset:37440
	v_cmp_ge_i32_e64 s[2:3], 0, v178
	v_cmp_ge_i32_e64 s[4:5], 1, v178
	v_cmp_ge_i32_e64 s[24:25], 2, v178
	v_cmp_ge_i32_e64 s[26:27], 3, v178
	v_cndmask_b32_e64 v32, v238, v32, s[2:3]
	v_cndmask_b32_e64 v33, v238, v33, s[4:5]
	v_cndmask_b32_e64 v34, v238, v34, s[24:25]
	v_cndmask_b32_e64 v35, v238, v35, s[26:27]
	v_cmp_ge_i32_e64 s[2:3], 8, v178
	v_cmp_ge_i32_e64 s[4:5], 9, v178
	v_cmp_ge_i32_e64 s[24:25], 10, v178
	v_cmp_ge_i32_e64 s[26:27], 11, v178
	v_cndmask_b32_e64 v36, v238, v36, s[2:3]
	v_cndmask_b32_e64 v37, v238, v37, s[4:5]
	v_cndmask_b32_e64 v38, v238, v38, s[24:25]
	v_cndmask_b32_e64 v39, v238, v39, s[26:27]
	v_mul_f32_e32 v32, 0x3e38aa3b, v32
	v_mul_f32_e32 v33, 0x3e38aa3b, v33
	v_mul_f32_e32 v34, 0x3e38aa3b, v34
	v_mul_f32_e32 v35, 0x3e38aa3b, v35
	v_mul_f32_e32 v36, 0x3e38aa3b, v36
	v_mul_f32_e32 v37, 0x3e38aa3b, v37
	v_mul_f32_e32 v38, 0x3e38aa3b, v38
	v_mul_f32_e32 v39, 0x3e38aa3b, v39
	v_exp_f32_e32 v32, v32
	v_exp_f32_e32 v33, v33
	v_exp_f32_e32 v34, v34
	v_exp_f32_e32 v35, v35
	v_exp_f32_e32 v36, v36
	v_exp_f32_e32 v37, v37
	v_exp_f32_e32 v38, v38
	v_exp_f32_e32 v39, v39
	v_add_f32_e32 v234, v32, v34
	v_add_f32_e32 v235, v33, v35
	v_add_f32_e32 v234, v234, v36
	v_add_f32_e32 v235, v235, v37
	v_add_f32_e32 v234, v234, v38
	v_add_f32_e32 v235, v235, v39
	v_cvt_pk_bf16_f32 v32, v32, v33
	v_cvt_pk_bf16_f32 v33, v34, v35
	v_cvt_pk_bf16_f32 v34, v36, v37
	v_cvt_pk_bf16_f32 v35, v38, v39
	v_cmp_ge_i32_e64 s[2:3], 16, v178
	v_cmp_ge_i32_e64 s[4:5], 17, v178
	s_waitcnt lgkmcnt(14)
	v_mfma_f32_32x32x16_bf16 v[16:31], v[186:189], v[32:35], v[16:31]
	v_cmp_ge_i32_e64 s[24:25], 18, v178
	v_cmp_ge_i32_e64 s[26:27], 19, v178
	v_cndmask_b32_e64 v40, v238, v40, s[2:3]
	v_cndmask_b32_e64 v41, v238, v41, s[4:5]
	v_cndmask_b32_e64 v42, v238, v42, s[24:25]
	v_cndmask_b32_e64 v43, v238, v43, s[26:27]
	s_waitcnt lgkmcnt(12)
	v_mfma_f32_32x32x16_bf16 v[0:15], v[190:193], v[32:35], v[0:15]
	v_cmp_ge_i32_e64 s[2:3], 24, v178
	v_cmp_ge_i32_e64 s[4:5], 25, v178
	v_cmp_ge_i32_e64 s[24:25], 26, v178
	v_cmp_ge_i32_e64 s[26:27], 27, v178
	v_cndmask_b32_e64 v44, v238, v44, s[2:3]
	v_cndmask_b32_e64 v45, v238, v45, s[4:5]
	v_cndmask_b32_e64 v46, v238, v46, s[24:25]
	v_cndmask_b32_e64 v47, v238, v47, s[26:27]
	v_mul_f32_e32 v40, 0x3e38aa3b, v40
	v_mul_f32_e32 v41, 0x3e38aa3b, v41
	v_mul_f32_e32 v42, 0x3e38aa3b, v42
	v_mul_f32_e32 v43, 0x3e38aa3b, v43
	v_mul_f32_e32 v44, 0x3e38aa3b, v44
	v_mul_f32_e32 v45, 0x3e38aa3b, v45
	v_mul_f32_e32 v46, 0x3e38aa3b, v46
	v_mul_f32_e32 v47, 0x3e38aa3b, v47
	v_exp_f32_e32 v40, v40
	v_exp_f32_e32 v41, v41
	v_exp_f32_e32 v42, v42
	v_exp_f32_e32 v43, v43
	v_exp_f32_e32 v44, v44
	v_exp_f32_e32 v45, v45
	v_exp_f32_e32 v46, v46
	v_exp_f32_e32 v47, v47
	v_add_f32_e32 v234, v234, v40
	v_add_f32_e32 v235, v235, v41
	v_add_f32_e32 v234, v234, v42
	v_add_f32_e32 v235, v235, v43
	v_add_f32_e32 v234, v234, v44
	v_add_f32_e32 v235, v235, v45
	v_add_f32_e32 v234, v234, v46
	v_add_f32_e32 v235, v235, v47
	v_cvt_pk_bf16_f32 v40, v40, v41
	v_cvt_pk_bf16_f32 v41, v42, v43
	v_cvt_pk_bf16_f32 v42, v44, v45
	v_cvt_pk_bf16_f32 v43, v46, v47
	v_cmp_ge_i32_e64 s[2:3], 32, v178
	v_cmp_ge_i32_e64 s[4:5], 33, v178
	s_waitcnt lgkmcnt(10)
	v_mfma_f32_32x32x16_bf16 v[16:31], v[194:197], v[40:43], v[16:31]
	v_cmp_ge_i32_e64 s[24:25], 34, v178
	v_cmp_ge_i32_e64 s[26:27], 35, v178
	v_cndmask_b32_e64 v48, v238, v48, s[2:3]
	v_cndmask_b32_e64 v49, v238, v49, s[4:5]
	v_cndmask_b32_e64 v50, v238, v50, s[24:25]
	v_cndmask_b32_e64 v51, v238, v51, s[26:27]
	s_waitcnt lgkmcnt(8)
	v_mfma_f32_32x32x16_bf16 v[0:15], v[198:201], v[40:43], v[0:15]
	v_cmp_ge_i32_e64 s[2:3], 40, v178
	v_cmp_ge_i32_e64 s[4:5], 41, v178
	v_cmp_ge_i32_e64 s[24:25], 42, v178
	v_cmp_ge_i32_e64 s[26:27], 43, v178
	v_cndmask_b32_e64 v52, v238, v52, s[2:3]
	v_cndmask_b32_e64 v53, v238, v53, s[4:5]
	v_cndmask_b32_e64 v54, v238, v54, s[24:25]
	v_cndmask_b32_e64 v55, v238, v55, s[26:27]
	v_mul_f32_e32 v48, 0x3e38aa3b, v48
	v_mul_f32_e32 v49, 0x3e38aa3b, v49
	v_mul_f32_e32 v50, 0x3e38aa3b, v50
	v_mul_f32_e32 v51, 0x3e38aa3b, v51
	v_mul_f32_e32 v52, 0x3e38aa3b, v52
	v_mul_f32_e32 v53, 0x3e38aa3b, v53
	v_mul_f32_e32 v54, 0x3e38aa3b, v54
	v_mul_f32_e32 v55, 0x3e38aa3b, v55
	v_exp_f32_e32 v48, v48
	v_exp_f32_e32 v49, v49
	v_exp_f32_e32 v50, v50
	v_exp_f32_e32 v51, v51
	v_exp_f32_e32 v52, v52
	v_exp_f32_e32 v53, v53
	v_exp_f32_e32 v54, v54
	v_exp_f32_e32 v55, v55
	v_add_f32_e32 v234, v234, v48
	v_add_f32_e32 v235, v235, v49
	v_add_f32_e32 v234, v234, v50
	v_add_f32_e32 v235, v235, v51
	v_add_f32_e32 v234, v234, v52
	v_add_f32_e32 v235, v235, v53
	v_add_f32_e32 v234, v234, v54
	v_add_f32_e32 v235, v235, v55
	v_cvt_pk_bf16_f32 v48, v48, v49
	v_cvt_pk_bf16_f32 v49, v50, v51
	v_cvt_pk_bf16_f32 v50, v52, v53
	v_cvt_pk_bf16_f32 v51, v54, v55
	v_cmp_ge_i32_e64 s[2:3], 48, v178
	v_cmp_ge_i32_e64 s[4:5], 49, v178
	s_waitcnt lgkmcnt(6)
	v_mfma_f32_32x32x16_bf16 v[16:31], v[202:205], v[48:51], v[16:31]
	v_cmp_ge_i32_e64 s[24:25], 50, v178
	v_cmp_ge_i32_e64 s[26:27], 51, v178
	v_cndmask_b32_e64 v56, v238, v56, s[2:3]
	v_cndmask_b32_e64 v57, v238, v57, s[4:5]
	v_cndmask_b32_e64 v58, v238, v58, s[24:25]
	v_cndmask_b32_e64 v59, v238, v59, s[26:27]
	s_waitcnt lgkmcnt(4)
	v_mfma_f32_32x32x16_bf16 v[0:15], v[206:209], v[48:51], v[0:15]
	v_cmp_ge_i32_e64 s[2:3], 56, v178
	v_cmp_ge_i32_e64 s[4:5], 57, v178
	v_cmp_ge_i32_e64 s[24:25], 58, v178
	v_cmp_ge_i32_e64 s[26:27], 59, v178
	v_cndmask_b32_e64 v60, v238, v60, s[2:3]
	v_cndmask_b32_e64 v61, v238, v61, s[4:5]
	v_cndmask_b32_e64 v62, v238, v62, s[24:25]
	v_cndmask_b32_e64 v63, v238, v63, s[26:27]
	v_mul_f32_e32 v56, 0x3e38aa3b, v56
	v_mul_f32_e32 v57, 0x3e38aa3b, v57
	v_mul_f32_e32 v58, 0x3e38aa3b, v58
	v_mul_f32_e32 v59, 0x3e38aa3b, v59
	v_mul_f32_e32 v60, 0x3e38aa3b, v60
	v_mul_f32_e32 v61, 0x3e38aa3b, v61
	v_mul_f32_e32 v62, 0x3e38aa3b, v62
	v_mul_f32_e32 v63, 0x3e38aa3b, v63
	v_exp_f32_e32 v56, v56
	v_exp_f32_e32 v57, v57
	v_exp_f32_e32 v58, v58
	v_exp_f32_e32 v59, v59
	v_exp_f32_e32 v60, v60
	v_exp_f32_e32 v61, v61
	v_exp_f32_e32 v62, v62
	v_exp_f32_e32 v63, v63
	v_add_f32_e32 v234, v234, v56
	v_add_f32_e32 v235, v235, v57
	v_add_f32_e32 v234, v234, v58
	v_add_f32_e32 v235, v235, v59
	v_add_f32_e32 v234, v234, v60
	v_add_f32_e32 v235, v235, v61
	v_add_f32_e32 v234, v234, v62
	v_add_f32_e32 v235, v235, v63
	v_cvt_pk_bf16_f32 v56, v56, v57
	v_cvt_pk_bf16_f32 v57, v58, v59
	v_cvt_pk_bf16_f32 v58, v60, v61
	v_cvt_pk_bf16_f32 v59, v62, v63
	s_nop 1
	s_waitcnt lgkmcnt(2)
	v_mfma_f32_32x32x16_bf16 v[16:31], v[210:213], v[56:59], v[16:31]
	s_waitcnt lgkmcnt(0)
	v_mfma_f32_32x32x16_bf16 v[0:15], v[214:217], v[56:59], v[0:15]
	v_add_f32_e32 v234, v234, v235
	v_add_f32_e32 v163, v163, v234
	v_cmp_lt_f32_e32 vcc, 0x43000000, v234
	s_cbranch_vccz .Lm2_nr_lA
	s_nop 15
	v_mov_b32_e32 v235, v234
	s_nop 1
	v_permlane32_swap_b32_e32 v234, v235
	v_add_f32_e32 v178, v234, v235
	v_cmp_lt_f32_e32 vcc, 0x43800000, v178
	v_frexp_exp_i32_f32_e32 v179, v178
	s_nop 1
	v_cndmask_b32_e32 v179, 0, v179, vcc
	v_cvt_f32_i32_e32 v180, v179
	v_sub_u32_e32 v179, 0, v179
	v_ldexp_f32 v178, 1.0, v179
	v_add_f32_e32 v168, v168, v180
	v_mul_f32_e32 v163, v163, v178
	v_mul_f32_e32 v0, v0, v178
	v_mul_f32_e32 v1, v1, v178
	v_mul_f32_e32 v2, v2, v178
	v_mul_f32_e32 v3, v3, v178
	v_mul_f32_e32 v4, v4, v178
	v_mul_f32_e32 v5, v5, v178
	v_mul_f32_e32 v6, v6, v178
	v_mul_f32_e32 v7, v7, v178
	v_mul_f32_e32 v8, v8, v178
	v_mul_f32_e32 v9, v9, v178
	v_mul_f32_e32 v10, v10, v178
	v_mul_f32_e32 v11, v11, v178
	v_mul_f32_e32 v12, v12, v178
	v_mul_f32_e32 v13, v13, v178
	v_mul_f32_e32 v14, v14, v178
	v_mul_f32_e32 v15, v15, v178
	v_mul_f32_e32 v16, v16, v178
	v_mul_f32_e32 v17, v17, v178
	v_mul_f32_e32 v18, v18, v178
	v_mul_f32_e32 v19, v19, v178
	v_mul_f32_e32 v20, v20, v178
	v_mul_f32_e32 v21, v21, v178
	v_mul_f32_e32 v22, v22, v178
	v_mul_f32_e32 v23, v23, v178
	v_mul_f32_e32 v24, v24, v178
	v_mul_f32_e32 v25, v25, v178
	v_mul_f32_e32 v26, v26, v178
	v_mul_f32_e32 v27, v27, v178
	v_mul_f32_e32 v28, v28, v178
	v_mul_f32_e32 v29, v29, v178
	v_mul_f32_e32 v30, v30, v178
	v_mul_f32_e32 v31, v31, v178
	v_mul_f32_e32 v218, 0xc0b17218, v168
	v_mov_b32_e32 v219, v218
	v_mov_b32_e32 v220, v218
	v_mov_b32_e32 v221, v218
	v_mov_b32_e32 v222, v218
	v_mov_b32_e32 v223, v218
	v_mov_b32_e32 v224, v218
	v_mov_b32_e32 v225, v218
	v_mov_b32_e32 v226, v218
	v_mov_b32_e32 v227, v218
	v_mov_b32_e32 v228, v218
	v_mov_b32_e32 v229, v218
	v_mov_b32_e32 v230, v218
	v_mov_b32_e32 v231, v218
	v_mov_b32_e32 v232, v218
	v_mov_b32_e32 v233, v218

.Lm2_highA:
	v_add_u32_e32 v236, v174, v162
	ds_read_b128 v[128:131], v236
	ds_read_b128 v[144:147], v236 offset:6656
	ds_read_b128 v[132:135], v236 offset:32
	ds_read_b128 v[148:151], v236 offset:6688
	ds_read_b128 v[136:139], v236 offset:64
	ds_read_b128 v[152:155], v236 offset:6720
	ds_read_b128 v[140:143], v236 offset:96
	ds_read_b128 v[156:159], v236 offset:6752
	v_add_u32_e32 v237, v176, v175
	s_sub_i32 s27, 0x80, s27
	v_sub_u32_e32 v178, s27, v177
	s_waitcnt lgkmcnt(7)
	v_mfma_f32_32x32x16_bf16 v[32:47], v[128:131], v[96:99], v[218:233]
	s_waitcnt lgkmcnt(6)
	v_mfma_f32_32x32x16_bf16 v[48:63], v[144:147], v[96:99], v[218:233]
	s_waitcnt lgkmcnt(5)
	v_mfma_f32_32x32x16_bf16 v[32:47], v[132:135], v[100:103], v[32:47]
	s_waitcnt lgkmcnt(4)
	v_mfma_f32_32x32x16_bf16 v[48:63], v[148:151], v[100:103], v[48:63]
	s_waitcnt lgkmcnt(3)
	v_mfma_f32_32x32x16_bf16 v[32:47], v[136:139], v[104:107], v[32:47]
	s_waitcnt lgkmcnt(2)
	v_mfma_f32_32x32x16_bf16 v[48:63], v[152:155], v[104:107], v[48:63]
	s_waitcnt lgkmcnt(1)
	v_mfma_f32_32x32x16_bf16 v[32:47], v[140:143], v[108:111], v[32:47]
	s_waitcnt lgkmcnt(0)
	v_mfma_f32_32x32x16_bf16 v[48:63], v[156:159], v[108:111], v[48:63]
	ds_read_b64_tr_b16 v[186:187], v237 offset:26624
	ds_read_b64_tr_b16 v[188:189], v237 offset:28160
	ds_read_b64_tr_b16 v[190:191], v237 offset:26688
	ds_read_b64_tr_b16 v[192:193], v237 offset:28224
	ds_read_b64_tr_b16 v[194:195], v237 offset:29696
	ds_read_b64_tr_b16 v[196:197], v237 offset:31232
	ds_read_b64_tr_b16 v[198:199], v237 offset:29760
	ds_read_b64_tr_b16 v[200:201], v237 offset:31296
	ds_read_b64_tr_b16 v[202:203], v237 offset:32768
	ds_read_b64_tr_b16 v[204:205], v237 offset:34304
	ds_read_b64_tr_b16 v[206:207], v237 offset:32832
	ds_read_b64_tr_b16 v[208:209], v237 offset:34368
	ds_read_b64_tr_b16 v[210:211], v237 offset:35840
	ds_read_b64_tr_b16 v[212:213], v237 offset:37376
	ds_read_b64_tr_b16 v[214:215], v237 offset:35904
	ds_read_b64_tr_b16 v[216:217], v237 offset:37440
	v_cmp_le_i32_e64 s[2:3], 0, v178
	v_cmp_le_i32_e64 s[4:5], 1, v178
	v_cmp_le_i32_e64 s[24:25], 2, v178
	v_cmp_le_i32_e64 s[26:27], 3, v178
	v_cndmask_b32_e64 v32, v238, v32, s[2:3]
	v_cndmask_b32_e64 v33, v238, v33, s[4:5]
	v_cndmask_b32_e64 v34, v238, v34, s[24:25]
	v_cndmask_b32_e64 v35, v238, v35, s[26:27]
	v_cmp_le_i32_e64 s[2:3], 8, v178
	v_cmp_le_i32_e64 s[4:5], 9, v178
	v_cmp_le_i32_e64 s[24:25], 10, v178
	v_cmp_le_i32_e64 s[26:27], 11, v178
	v_cndmask_b32_e64 v36, v238, v36, s[2:3]
	v_cndmask_b32_e64 v37, v238, v37, s[4:5]
	v_cndmask_b32_e64 v38, v238, v38, s[24:25]
	v_cndmask_b32_e64 v39, v238, v39, s[26:27]
	v_mul_f32_e32 v32, 0x3e38aa3b, v32
	v_mul_f32_e32 v33, 0x3e38aa3b, v33
	v_mul_f32_e32 v34, 0x3e38aa3b, v34
	v_mul_f32_e32 v35, 0x3e38aa3b, v35
	v_mul_f32_e32 v36, 0x3e38aa3b, v36
	v_mul_f32_e32 v37, 0x3e38aa3b, v37
	v_mul_f32_e32 v38, 0x3e38aa3b, v38
	v_mul_f32_e32 v39, 0x3e38aa3b, v39
	v_exp_f32_e32 v32, v32
	v_exp_f32_e32 v33, v33
	v_exp_f32_e32 v34, v34
	v_exp_f32_e32 v35, v35
	v_exp_f32_e32 v36, v36
	v_exp_f32_e32 v37, v37
	v_exp_f32_e32 v38, v38
	v_exp_f32_e32 v39, v39
	v_add_f32_e32 v234, v32, v34
	v_add_f32_e32 v235, v33, v35
	v_add_f32_e32 v234, v234, v36
	v_add_f32_e32 v235, v235, v37
	v_add_f32_e32 v234, v234, v38
	v_add_f32_e32 v235, v235, v39
	v_cvt_pk_bf16_f32 v32, v32, v33
	v_cvt_pk_bf16_f32 v33, v34, v35
	v_cvt_pk_bf16_f32 v34, v36, v37
	v_cvt_pk_bf16_f32 v35, v38, v39
	v_cmp_le_i32_e64 s[2:3], 16, v178
	v_cmp_le_i32_e64 s[4:5], 17, v178
	s_waitcnt lgkmcnt(14)
	v_mfma_f32_32x32x16_bf16 v[16:31], v[186:189], v[32:35], v[16:31]
	v_cmp_le_i32_e64 s[24:25], 18, v178
	v_cmp_le_i32_e64 s[26:27], 19, v178
	v_cndmask_b32_e64 v40, v238, v40, s[2:3]
	v_cndmask_b32_e64 v41, v238, v41, s[4:5]
	v_cndmask_b32_e64 v42, v238, v42, s[24:25]
	v_cndmask_b32_e64 v43, v238, v43, s[26:27]
	s_waitcnt lgkmcnt(12)
	v_mfma_f32_32x32x16_bf16 v[0:15], v[190:193], v[32:35], v[0:15]
	v_cmp_le_i32_e64 s[2:3], 24, v178
	v_cmp_le_i32_e64 s[4:5], 25, v178
	v_cmp_le_i32_e64 s[24:25], 26, v178
	v_cmp_le_i32_e64 s[26:27], 27, v178
	v_cndmask_b32_e64 v44, v238, v44, s[2:3]
	v_cndmask_b32_e64 v45, v238, v45, s[4:5]
	v_cndmask_b32_e64 v46, v238, v46, s[24:25]
	v_cndmask_b32_e64 v47, v238, v47, s[26:27]
	v_mul_f32_e32 v40, 0x3e38aa3b, v40
	v_mul_f32_e32 v41, 0x3e38aa3b, v41
	v_mul_f32_e32 v42, 0x3e38aa3b, v42
	v_mul_f32_e32 v43, 0x3e38aa3b, v43
	v_mul_f32_e32 v44, 0x3e38aa3b, v44
	v_mul_f32_e32 v45, 0x3e38aa3b, v45
	v_mul_f32_e32 v46, 0x3e38aa3b, v46
	v_mul_f32_e32 v47, 0x3e38aa3b, v47
	v_exp_f32_e32 v40, v40
	v_exp_f32_e32 v41, v41
	v_exp_f32_e32 v42, v42
	v_exp_f32_e32 v43, v43
	v_exp_f32_e32 v44, v44
	v_exp_f32_e32 v45, v45
	v_exp_f32_e32 v46, v46
	v_exp_f32_e32 v47, v47
	v_add_f32_e32 v234, v234, v40
	v_add_f32_e32 v235, v235, v41
	v_add_f32_e32 v234, v234, v42
	v_add_f32_e32 v235, v235, v43
	v_add_f32_e32 v234, v234, v44
	v_add_f32_e32 v235, v235, v45
	v_add_f32_e32 v234, v234, v46
	v_add_f32_e32 v235, v235, v47
	v_cvt_pk_bf16_f32 v40, v40, v41
	v_cvt_pk_bf16_f32 v41, v42, v43
	v_cvt_pk_bf16_f32 v42, v44, v45
	v_cvt_pk_bf16_f32 v43, v46, v47
	v_cmp_le_i32_e64 s[2:3], 32, v178
	v_cmp_le_i32_e64 s[4:5], 33, v178
	s_waitcnt lgkmcnt(10)
	v_mfma_f32_32x32x16_bf16 v[16:31], v[194:197], v[40:43], v[16:31]
	v_cmp_le_i32_e64 s[24:25], 34, v178
	v_cmp_le_i32_e64 s[26:27], 35, v178
	v_cndmask_b32_e64 v48, v238, v48, s[2:3]
	v_cndmask_b32_e64 v49, v238, v49, s[4:5]
	v_cndmask_b32_e64 v50, v238, v50, s[24:25]
	v_cndmask_b32_e64 v51, v238, v51, s[26:27]
	s_waitcnt lgkmcnt(8)
	v_mfma_f32_32x32x16_bf16 v[0:15], v[198:201], v[40:43], v[0:15]
	v_cmp_le_i32_e64 s[2:3], 40, v178
	v_cmp_le_i32_e64 s[4:5], 41, v178
	v_cmp_le_i32_e64 s[24:25], 42, v178
	v_cmp_le_i32_e64 s[26:27], 43, v178
	v_cndmask_b32_e64 v52, v238, v52, s[2:3]
	v_cndmask_b32_e64 v53, v238, v53, s[4:5]
	v_cndmask_b32_e64 v54, v238, v54, s[24:25]
	v_cndmask_b32_e64 v55, v238, v55, s[26:27]
	v_mul_f32_e32 v48, 0x3e38aa3b, v48
	v_mul_f32_e32 v49, 0x3e38aa3b, v49
	v_mul_f32_e32 v50, 0x3e38aa3b, v50
	v_mul_f32_e32 v51, 0x3e38aa3b, v51
	v_mul_f32_e32 v52, 0x3e38aa3b, v52
	v_mul_f32_e32 v53, 0x3e38aa3b, v53
	v_mul_f32_e32 v54, 0x3e38aa3b, v54
	v_mul_f32_e32 v55, 0x3e38aa3b, v55
	v_exp_f32_e32 v48, v48
	v_exp_f32_e32 v49, v49
	v_exp_f32_e32 v50, v50
	v_exp_f32_e32 v51, v51
	v_exp_f32_e32 v52, v52
	v_exp_f32_e32 v53, v53
	v_exp_f32_e32 v54, v54
	v_exp_f32_e32 v55, v55
	v_add_f32_e32 v234, v234, v48
	v_add_f32_e32 v235, v235, v49
	v_add_f32_e32 v234, v234, v50
	v_add_f32_e32 v235, v235, v51
	v_add_f32_e32 v234, v234, v52
	v_add_f32_e32 v235, v235, v53
	v_add_f32_e32 v234, v234, v54
	v_add_f32_e32 v235, v235, v55
	v_cvt_pk_bf16_f32 v48, v48, v49
	v_cvt_pk_bf16_f32 v49, v50, v51
	v_cvt_pk_bf16_f32 v50, v52, v53
	v_cvt_pk_bf16_f32 v51, v54, v55
	v_cmp_le_i32_e64 s[2:3], 48, v178
	v_cmp_le_i32_e64 s[4:5], 49, v178
	s_waitcnt lgkmcnt(6)
	v_mfma_f32_32x32x16_bf16 v[16:31], v[202:205], v[48:51], v[16:31]
	v_cmp_le_i32_e64 s[24:25], 50, v178
	v_cmp_le_i32_e64 s[26:27], 51, v178
	v_cndmask_b32_e64 v56, v238, v56, s[2:3]
	v_cndmask_b32_e64 v57, v238, v57, s[4:5]
	v_cndmask_b32_e64 v58, v238, v58, s[24:25]
	v_cndmask_b32_e64 v59, v238, v59, s[26:27]
	s_waitcnt lgkmcnt(4)
	v_mfma_f32_32x32x16_bf16 v[0:15], v[206:209], v[48:51], v[0:15]
	v_cmp_le_i32_e64 s[2:3], 56, v178
	v_cmp_le_i32_e64 s[4:5], 57, v178
	v_cmp_le_i32_e64 s[24:25], 58, v178
	v_cmp_le_i32_e64 s[26:27], 59, v178
	v_cndmask_b32_e64 v60, v238, v60, s[2:3]
	v_cndmask_b32_e64 v61, v238, v61, s[4:5]
	v_cndmask_b32_e64 v62, v238, v62, s[24:25]
	v_cndmask_b32_e64 v63, v238, v63, s[26:27]
	v_mul_f32_e32 v56, 0x3e38aa3b, v56
	v_mul_f32_e32 v57, 0x3e38aa3b, v57
	v_mul_f32_e32 v58, 0x3e38aa3b, v58
	v_mul_f32_e32 v59, 0x3e38aa3b, v59
	v_mul_f32_e32 v60, 0x3e38aa3b, v60
	v_mul_f32_e32 v61, 0x3e38aa3b, v61
	v_mul_f32_e32 v62, 0x3e38aa3b, v62
	v_mul_f32_e32 v63, 0x3e38aa3b, v63
	v_exp_f32_e32 v56, v56
	v_exp_f32_e32 v57, v57
	v_exp_f32_e32 v58, v58
	v_exp_f32_e32 v59, v59
	v_exp_f32_e32 v60, v60
	v_exp_f32_e32 v61, v61
	v_exp_f32_e32 v62, v62
	v_exp_f32_e32 v63, v63
	v_add_f32_e32 v234, v234, v56
	v_add_f32_e32 v235, v235, v57
	v_add_f32_e32 v234, v234, v58
	v_add_f32_e32 v235, v235, v59
	v_add_f32_e32 v234, v234, v60
	v_add_f32_e32 v235, v235, v61
	v_add_f32_e32 v234, v234, v62
	v_add_f32_e32 v235, v235, v63
	v_cvt_pk_bf16_f32 v56, v56, v57
	v_cvt_pk_bf16_f32 v57, v58, v59
	v_cvt_pk_bf16_f32 v58, v60, v61
	v_cvt_pk_bf16_f32 v59, v62, v63
	s_nop 1
	s_waitcnt lgkmcnt(2)
	v_mfma_f32_32x32x16_bf16 v[16:31], v[210:213], v[56:59], v[16:31]
	s_waitcnt lgkmcnt(0)
	v_mfma_f32_32x32x16_bf16 v[0:15], v[214:217], v[56:59], v[0:15]
	v_add_f32_e32 v234, v234, v235
	v_add_f32_e32 v163, v163, v234
	v_cmp_lt_f32_e32 vcc, 0x43000000, v234
	s_cbranch_vccz .Lm2_nr_hA
	s_nop 15
	v_mov_b32_e32 v235, v234
	s_nop 1
	v_permlane32_swap_b32_e32 v234, v235
	v_add_f32_e32 v178, v234, v235
	v_cmp_lt_f32_e32 vcc, 0x43800000, v178
	v_frexp_exp_i32_f32_e32 v179, v178
	s_nop 1
	v_cndmask_b32_e32 v179, 0, v179, vcc
	v_cvt_f32_i32_e32 v180, v179
	v_sub_u32_e32 v179, 0, v179
	v_ldexp_f32 v178, 1.0, v179
	v_add_f32_e32 v168, v168, v180
	v_mul_f32_e32 v163, v163, v178
	v_mul_f32_e32 v0, v0, v178
	v_mul_f32_e32 v1, v1, v178
	v_mul_f32_e32 v2, v2, v178
	v_mul_f32_e32 v3, v3, v178
	v_mul_f32_e32 v4, v4, v178
	v_mul_f32_e32 v5, v5, v178
	v_mul_f32_e32 v6, v6, v178
	v_mul_f32_e32 v7, v7, v178
	v_mul_f32_e32 v8, v8, v178
	v_mul_f32_e32 v9, v9, v178
	v_mul_f32_e32 v10, v10, v178
	v_mul_f32_e32 v11, v11, v178
	v_mul_f32_e32 v12, v12, v178
	v_mul_f32_e32 v13, v13, v178
	v_mul_f32_e32 v14, v14, v178
	v_mul_f32_e32 v15, v15, v178
	v_mul_f32_e32 v16, v16, v178
	v_mul_f32_e32 v17, v17, v178
	v_mul_f32_e32 v18, v18, v178
	v_mul_f32_e32 v19, v19, v178
	v_mul_f32_e32 v20, v20, v178
	v_mul_f32_e32 v21, v21, v178
	v_mul_f32_e32 v22, v22, v178
	v_mul_f32_e32 v23, v23, v178
	v_mul_f32_e32 v24, v24, v178
	v_mul_f32_e32 v25, v25, v178
	v_mul_f32_e32 v26, v26, v178
	v_mul_f32_e32 v27, v27, v178
	v_mul_f32_e32 v28, v28, v178
	v_mul_f32_e32 v29, v29, v178
	v_mul_f32_e32 v30, v30, v178
	v_mul_f32_e32 v31, v31, v178
	v_mul_f32_e32 v218, 0xc0b17218, v168
	v_mov_b32_e32 v219, v218
	v_mov_b32_e32 v220, v218
	v_mov_b32_e32 v221, v218
	v_mov_b32_e32 v222, v218
	v_mov_b32_e32 v223, v218
	v_mov_b32_e32 v224, v218
	v_mov_b32_e32 v225, v218
	v_mov_b32_e32 v226, v218
	v_mov_b32_e32 v227, v218
	v_mov_b32_e32 v228, v218
	v_mov_b32_e32 v229, v218
	v_mov_b32_e32 v230, v218
	v_mov_b32_e32 v231, v218
	v_mov_b32_e32 v232, v218
	v_mov_b32_e32 v233, v218
.Lm2_nr_hA:
.Lm2_doneA:
	s_add_i32 s24, s19, -2
	s_cmp_ge_i32 s24, s6
	s_cbranch_scc1 .Lm2_nwA
	s_waitcnt vmcnt(3)
	ds_write_b128 v172, v[112:115] offset:13312
	s_waitcnt vmcnt(2)
	ds_write_b128 v173, v[116:119] offset:38912
.Lm2_nwA:
	s_waitcnt lgkmcnt(0)
	s_barrier
	s_add_i32 s24, s19, 0
	s_min_i32 s24, s24, s7
	s_cmp_lt_i32 s24, s14
	s_cselect_b32 s25, s15, s20
	s_cselect_b32 s26, s13, s16
	s_add_i32 s25, s25, s24
	s_lshl_b32 s25, s25, 6
	s_add_i32 s26, s26, s25
	v_add_u32_e32 v236, s26, v161
	v_mad_i64_i32 v[236:237], s[98:99], v236, s33, v[164:165]
	global_load_dwordx4 v[112:115], v[236:237], off
	v_add_u32_e32 v236, s26, v171
	v_mad_i64_i32 v[236:237], s[98:99], v236, s33, v[166:167]
	global_load_dwordx4 v[116:119], v[236:237], off
	s_add_i32 s24, s19, -2
	s_cmp_ge_i32 s24, s6
	s_cbranch_scc1 .Lm2_doneB
	s_cmp_ge_i32 s24, s14
	s_cbranch_scc1 .Lm2_fullB
	s_add_i32 s27, s21, 64
	s_add_i32 s25, s27, 63
	s_cmp_lt_i32 s25, s17
	s_cbranch_scc1 .Lm2_doneB
	s_cmp_gt_i32 s27, s18
	s_cbranch_scc1 .Lm2_doneB
	s_add_i32 s25, s17, 31
	s_cmp_lt_i32 s27, s25
	s_cbranch_scc1 .Lm2_lowB
	s_add_i32 s25, s17, 0xc1
	s_cmp_gt_i32 s27, s25
	s_cbranch_scc1 .Lm2_highB
.Lm2_fullB:
	v_add_u32_e32 v236, v174, v162
	ds_read_b128 v[128:131], v236 offset:13312
	ds_read_b128 v[144:147], v236 offset:19968
	ds_read_b128 v[132:135], v236 offset:13344
	ds_read_b128 v[148:151], v236 offset:20000
	ds_read_b128 v[136:139], v236 offset:13376
	ds_read_b128 v[152:155], v236 offset:20032
	ds_read_b128 v[140:143], v236 offset:13408
	ds_read_b128 v[156:159], v236 offset:20064
	v_add_u32_e32 v237, v176, v175
	s_waitcnt lgkmcnt(7)
	v_mfma_f32_32x32x16_bf16 v[32:47], v[128:131], v[96:99], v[218:233]
	s_waitcnt lgkmcnt(6)
	v_mfma_f32_32x32x16_bf16 v[48:63], v[144:147], v[96:99], v[218:233]
	s_waitcnt lgkmcnt(5)
	v_mfma_f32_32x32x16_bf16 v[32:47], v[132:135], v[100:103], v[32:47]
	s_waitcnt lgkmcnt(4)
	v_mfma_f32_32x32x16_bf16 v[48:63], v[148:151], v[100:103], v[48:63]
	s_waitcnt lgkmcnt(3)
	v_mfma_f32_32x32x16_bf16 v[32:47], v[136:139], v[104:107], v[32:47]
	s_waitcnt lgkmcnt(2)
	v_mfma_f32_32x32x16_bf16 v[48:63], v[152:155], v[104:107], v[48:63]
	s_waitcnt lgkmcnt(1)
	v_mfma_f32_32x32x16_bf16 v[32:47], v[140:143], v[108:111], v[32:47]
	s_waitcnt lgkmcnt(0)
	v_mfma_f32_32x32x16_bf16 v[48:63], v[156:159], v[108:111], v[48:63]
	ds_read_b64_tr_b16 v[186:187], v237 offset:38912
	ds_read_b64_tr_b16 v[188:189], v237 offset:40448
	ds_read_b64_tr_b16 v[190:191], v237 offset:38976
	ds_read_b64_tr_b16 v[192:193], v237 offset:40512
	ds_read_b64_tr_b16 v[194:195], v237 offset:41984
	ds_read_b64_tr_b16 v[196:197], v237 offset:43520
	ds_read_b64_tr_b16 v[198:199], v237 offset:42048
	ds_read_b64_tr_b16 v[200:201], v237 offset:43584
	ds_read_b64_tr_b16 v[202:203], v237 offset:45056
	ds_read_b64_tr_b16 v[204:205], v237 offset:46592
	ds_read_b64_tr_b16 v[206:207], v237 offset:45120
	ds_read_b64_tr_b16 v[208:209], v237 offset:46656
	ds_read_b64_tr_b16 v[210:211], v237 offset:48128
	ds_read_b64_tr_b16 v[212:213], v237 offset:49664
	ds_read_b64_tr_b16 v[214:215], v237 offset:48192
	ds_read_b64_tr_b16 v[216:217], v237 offset:49728
	v_mul_f32_e32 v32, 0x3e38aa3b, v32
	v_mul_f32_e32 v33, 0x3e38aa3b, v33
	v_mul_f32_e32 v34, 0x3e38aa3b, v34
	v_mul_f32_e32 v35, 0x3e38aa3b, v35
	v_mul_f32_e32 v36, 0x3e38aa3b, v36
	v_mul_f32_e32 v37, 0x3e38aa3b, v37
	v_mul_f32_e32 v38, 0x3e38aa3b, v38
	v_mul_f32_e32 v39, 0x3e38aa3b, v39
	v_exp_f32_e32 v32, v32
	v_exp_f32_e32 v33, v33
	v_exp_f32_e32 v34, v34
	v_exp_f32_e32 v35, v35
	v_exp_f32_e32 v36, v36
	v_exp_f32_e32 v37, v37
	v_exp_f32_e32 v38, v38
	v_exp_f32_e32 v39, v39
	v_add_f32_e32 v234, v32, v34
	v_add_f32_e32 v235, v33, v35
	v_add_f32_e32 v234, v234, v36
	v_add_f32_e32 v235, v235, v37
	v_add_f32_e32 v234, v234, v38
	v_add_f32_e32 v235, v235, v39
	v_cvt_pk_bf16_f32 v32, v32, v33
	v_cvt_pk_bf16_f32 v33, v34, v35
	v_cvt_pk_bf16_f32 v34, v36, v37
	v_cvt_pk_bf16_f32 v35, v38, v39
	v_mul_f32_e32 v40, 0x3e38aa3b, v40
	v_mul_f32_e32 v41, 0x3e38aa3b, v41
	s_waitcnt lgkmcnt(14)
	v_mfma_f32_32x32x16_bf16 v[16:31], v[186:189], v[32:35], v[16:31]
	v_mul_f32_e32 v42, 0x3e38aa3b, v42
	v_mul_f32_e32 v43, 0x3e38aa3b, v43
	v_mul_f32_e32 v44, 0x3e38aa3b, v44
	v_mul_f32_e32 v45, 0x3e38aa3b, v45
	v_mul_f32_e32 v46, 0x3e38aa3b, v46
	v_mul_f32_e32 v47, 0x3e38aa3b, v47
	s_waitcnt lgkmcnt(12)
	v_mfma_f32_32x32x16_bf16 v[0:15], v[190:193], v[32:35], v[0:15]
	v_exp_f32_e32 v40, v40
	v_exp_f32_e32 v41, v41
	v_exp_f32_e32 v42, v42
	v_exp_f32_e32 v43, v43
	v_exp_f32_e32 v44, v44
	v_exp_f32_e32 v45, v45
	v_exp_f32_e32 v46, v46
	v_exp_f32_e32 v47, v47
	v_add_f32_e32 v234, v234, v40
	v_add_f32_e32 v235, v235, v41
	v_add_f32_e32 v234, v234, v42
	v_add_f32_e32 v235, v235, v43
	v_add_f32_e32 v234, v234, v44
	v_add_f32_e32 v235, v235, v45
	v_add_f32_e32 v234, v234, v46
	v_add_f32_e32 v235, v235, v47
	v_cvt_pk_bf16_f32 v40, v40, v41
	v_cvt_pk_bf16_f32 v41, v42, v43
	v_cvt_pk_bf16_f32 v42, v44, v45
	v_cvt_pk_bf16_f32 v43, v46, v47
	v_mul_f32_e32 v48, 0x3e38aa3b, v48
	v_mul_f32_e32 v49, 0x3e38aa3b, v49
	s_waitcnt lgkmcnt(10)
	v_mfma_f32_32x32x16_bf16 v[16:31], v[194:197], v[40:43], v[16:31]
	v_mul_f32_e32 v50, 0x3e38aa3b, v50
	v_mul_f32_e32 v51, 0x3e38aa3b, v51
	v_mul_f32_e32 v52, 0x3e38aa3b, v52
	v_mul_f32_e32 v53, 0x3e38aa3b, v53
	v_mul_f32_e32 v54, 0x3e38aa3b, v54
	v_mul_f32_e32 v55, 0x3e38aa3b, v55
	s_waitcnt lgkmcnt(8)
	v_mfma_f32_32x32x16_bf16 v[0:15], v[198:201], v[40:43], v[0:15]
	v_exp_f32_e32 v48, v48
	v_exp_f32_e32 v49, v49
	v_exp_f32_e32 v50, v50
	v_exp_f32_e32 v51, v51
	v_exp_f32_e32 v52, v52
	v_exp_f32_e32 v53, v53
	v_exp_f32_e32 v54, v54
	v_exp_f32_e32 v55, v55
	v_add_f32_e32 v234, v234, v48
	v_add_f32_e32 v235, v235, v49
	v_add_f32_e32 v234, v234, v50
	v_add_f32_e32 v235, v235, v51
	v_add_f32_e32 v234, v234, v52
	v_add_f32_e32 v235, v235, v53
	v_add_f32_e32 v234, v234, v54
	v_add_f32_e32 v235, v235, v55
	v_cvt_pk_bf16_f32 v48, v48, v49
	v_cvt_pk_bf16_f32 v49, v50, v51
	v_cvt_pk_bf16_f32 v50, v52, v53
	v_cvt_pk_bf16_f32 v51, v54, v55
	v_mul_f32_e32 v56, 0x3e38aa3b, v56
	v_mul_f32_e32 v57, 0x3e38aa3b, v57
	s_waitcnt lgkmcnt(6)
	v_mfma_f32_32x32x16_bf16 v[16:31], v[202:205], v[48:51], v[16:31]
	v_mul_f32_e32 v58, 0x3e38aa3b, v58
	v_mul_f32_e32 v59, 0x3e38aa3b, v59
	v_mul_f32_e32 v60, 0x3e38aa3b, v60
	v_mul_f32_e32 v61, 0x3e38aa3b, v61
	v_mul_f32_e32 v62, 0x3e38aa3b, v62
	v_mul_f32_e32 v63, 0x3e38aa3b, v63
	s_waitcnt lgkmcnt(4)
	v_mfma_f32_32x32x16_bf16 v[0:15], v[206:209], v[48:51], v[0:15]
	v_exp_f32_e32 v56, v56
	v_exp_f32_e32 v57, v57
	v_exp_f32_e32 v58, v58
	v_exp_f32_e32 v59, v59
	v_exp_f32_e32 v60, v60
	v_exp_f32_e32 v61, v61
	v_exp_f32_e32 v62, v62
	v_exp_f32_e32 v63, v63
	v_add_f32_e32 v234, v234, v56
	v_add_f32_e32 v235, v235, v57
	v_add_f32_e32 v234, v234, v58
	v_add_f32_e32 v235, v235, v59
	v_add_f32_e32 v234, v234, v60
	v_add_f32_e32 v235, v235, v61
	v_add_f32_e32 v234, v234, v62
	v_add_f32_e32 v235, v235, v63
	v_cvt_pk_bf16_f32 v56, v56, v57
	v_cvt_pk_bf16_f32 v57, v58, v59
	v_cvt_pk_bf16_f32 v58, v60, v61
	v_cvt_pk_bf16_f32 v59, v62, v63
	s_nop 1
	s_waitcnt lgkmcnt(2)
	v_mfma_f32_32x32x16_bf16 v[16:31], v[210:213], v[56:59], v[16:31]
	s_waitcnt lgkmcnt(0)
	v_mfma_f32_32x32x16_bf16 v[0:15], v[214:217], v[56:59], v[0:15]
	v_add_f32_e32 v234, v234, v235
	v_add_f32_e32 v163, v163, v234
	v_cmp_lt_f32_e32 vcc, 0x43000000, v234
	s_cbranch_vccz .Lm2_nr_fB
	s_nop 15
	v_mov_b32_e32 v235, v234
	s_nop 1
	v_permlane32_swap_b32_e32 v234, v235
	v_add_f32_e32 v178, v234, v235
	v_cmp_lt_f32_e32 vcc, 0x43800000, v178
	v_frexp_exp_i32_f32_e32 v179, v178
	s_nop 1
	v_cndmask_b32_e32 v179, 0, v179, vcc
	v_cvt_f32_i32_e32 v180, v179
	v_sub_u32_e32 v179, 0, v179
	v_ldexp_f32 v178, 1.0, v179
	v_add_f32_e32 v168, v168, v180
	v_mul_f32_e32 v163, v163, v178
	v_mul_f32_e32 v0, v0, v178
	v_mul_f32_e32 v1, v1, v178
	v_mul_f32_e32 v2, v2, v178
	v_mul_f32_e32 v3, v3, v178
	v_mul_f32_e32 v4, v4, v178
	v_mul_f32_e32 v5, v5, v178
	v_mul_f32_e32 v6, v6, v178
	v_mul_f32_e32 v7, v7, v178
	v_mul_f32_e32 v8, v8, v178
	v_mul_f32_e32 v9, v9, v178
	v_mul_f32_e32 v10, v10, v178
	v_mul_f32_e32 v11, v11, v178
	v_mul_f32_e32 v12, v12, v178
	v_mul_f32_e32 v13, v13, v178
	v_mul_f32_e32 v14, v14, v178
	v_mul_f32_e32 v15, v15, v178
	v_mul_f32_e32 v16, v16, v178
	v_mul_f32_e32 v17, v17, v178
	v_mul_f32_e32 v18, v18, v178
	v_mul_f32_e32 v19, v19, v178
	v_mul_f32_e32 v20, v20, v178
	v_mul_f32_e32 v21, v21, v178
	v_mul_f32_e32 v22, v22, v178
	v_mul_f32_e32 v23, v23, v178
	v_mul_f32_e32 v24, v24, v178
	v_mul_f32_e32 v25, v25, v178
	v_mul_f32_e32 v26, v26, v178
	v_mul_f32_e32 v27, v27, v178
	v_mul_f32_e32 v28, v28, v178
	v_mul_f32_e32 v29, v29, v178
	v_mul_f32_e32 v30, v30, v178
	v_mul_f32_e32 v31, v31, v178
	v_mul_f32_e32 v218, 0xc0b17218, v168
	v_mov_b32_e32 v219, v218
	v_mov_b32_e32 v220, v218
	v_mov_b32_e32 v221, v218
	v_mov_b32_e32 v222, v218
	v_mov_b32_e32 v223, v218
	v_mov_b32_e32 v224, v218
	v_mov_b32_e32 v225, v218
	v_mov_b32_e32 v226, v218
	v_mov_b32_e32 v227, v218
	v_mov_b32_e32 v228, v218
	v_mov_b32_e32 v229, v218
	v_mov_b32_e32 v230, v218
	v_mov_b32_e32 v231, v218
	v_mov_b32_e32 v232, v218
	v_mov_b32_e32 v233, v218

.Lm2_lowB:
	v_add_u32_e32 v236, v174, v162
	ds_read_b128 v[128:131], v236 offset:13312
	ds_read_b128 v[144:147], v236 offset:19968
	ds_read_b128 v[132:135], v236 offset:13344
	ds_read_b128 v[148:151], v236 offset:20000
	ds_read_b128 v[136:139], v236 offset:13376
	ds_read_b128 v[152:155], v236 offset:20032
	ds_read_b128 v[140:143], v236 offset:13408
	ds_read_b128 v[156:159], v236 offset:20064
	v_add_u32_e32 v237, v176, v175
	s_add_i32 s27, s27, 0x80
	v_add_u32_e32 v178, s27, v177
	v_sub_u32_e32 v178, 0, v178
	s_waitcnt lgkmcnt(7)
	v_mfma_f32_32x32x16_bf16 v[32:47], v[128:131], v[96:99], v[218:233]
	s_waitcnt lgkmcnt(6)
	v_mfma_f32_32x32x16_bf16 v[48:63], v[144:147], v[96:99], v[218:233]
	s_waitcnt lgkmcnt(5)
	v_mfma_f32_32x32x16_bf16 v[32:47], v[132:135], v[100:103], v[32:47]
	s_waitcnt lgkmcnt(4)
	v_mfma_f32_32x32x16_bf16 v[48:63], v[148:151], v[100:103], v[48:63]
	s_waitcnt lgkmcnt(3)
	v_mfma_f32_32x32x16_bf16 v[32:47], v[136:139], v[104:107], v[32:47]
	s_waitcnt lgkmcnt(2)
	v_mfma_f32_32x32x16_bf16 v[48:63], v[152:155], v[104:107], v[48:63]
	s_waitcnt lgkmcnt(1)
	v_mfma_f32_32x32x16_bf16 v[32:47], v[140:143], v[108:111], v[32:47]
	s_waitcnt lgkmcnt(0)
	v_mfma_f32_32x32x16_bf16 v[48:63], v[156:159], v[108:111], v[48:63]
	ds_read_b64_tr_b16 v[186:187], v237 offset:38912
	ds_read_b64_tr_b16 v[188:189], v237 offset:40448
	ds_read_b64_tr_b16 v[190:191], v237 offset:38976
	ds_read_b64_tr_b16 v[192:193], v237 offset:40512
	ds_read_b64_tr_b16 v[194:195], v237 offset:41984
	ds_read_b64_tr_b16 v[196:197], v237 offset:43520
	ds_read_b64_tr_b16 v[198:199], v237 offset:42048
	ds_read_b64_tr_b16 v[200:201], v237 offset:43584
	ds_read_b64_tr_b16 v[202:203], v237 offset:45056
	ds_read_b64_tr_b16 v[204:205], v237 offset:46592
	ds_read_b64_tr_b16 v[206:207], v237 offset:45120
	ds_read_b64_tr_b16 v[208:209], v237 offset:46656
	ds_read_b64_tr_b16 v[210:211], v237 offset:48128
	ds_read_b64_tr_b16 v[212:213], v237 offset:49664
	ds_read_b64_tr_b16 v[214:215], v237 offset:48192
	ds_read_b64_tr_b16 v[216:217], v237 offset:49728
	v_cmp_ge_i32_e64 s[2:3], 0, v178
	v_cmp_ge_i32_e64 s[4:5], 1, v178
	v_cmp_ge_i32_e64 s[24:25], 2, v178
	v_cmp_ge_i32_e64 s[26:27], 3, v178
	v_cndmask_b32_e64 v32, v238, v32, s[2:3]
	v_cndmask_b32_e64 v33, v238, v33, s[4:5]
	v_cndmask_b32_e64 v34, v238, v34, s[24:25]
	v_cndmask_b32_e64 v35, v238, v35, s[26:27]
	v_cmp_ge_i32_e64 s[2:3], 8, v178
	v_cmp_ge_i32_e64 s[4:5], 9, v178
	v_cmp_ge_i32_e64 s[24:25], 10, v178
	v_cmp_ge_i32_e64 s[26:27], 11, v178
	v_cndmask_b32_e64 v36, v238, v36, s[2:3]
	v_cndmask_b32_e64 v37, v238, v37, s[4:5]
	v_cndmask_b32_e64 v38, v238, v38, s[24:25]
	v_cndmask_b32_e64 v39, v238, v39, s[26:27]
	v_mul_f32_e32 v32, 0x3e38aa3b, v32
	v_mul_f32_e32 v33, 0x3e38aa3b, v33
	v_mul_f32_e32 v34, 0x3e38aa3b, v34
	v_mul_f32_e32 v35, 0x3e38aa3b, v35
	v_mul_f32_e32 v36, 0x3e38aa3b, v36
	v_mul_f32_e32 v37, 0x3e38aa3b, v37
	v_mul_f32_e32 v38, 0x3e38aa3b, v38
	v_mul_f32_e32 v39, 0x3e38aa3b, v39
	v_exp_f32_e32 v32, v32
	v_exp_f32_e32 v33, v33
	v_exp_f32_e32 v34, v34
	v_exp_f32_e32 v35, v35
	v_exp_f32_e32 v36, v36
	v_exp_f32_e32 v37, v37
	v_exp_f32_e32 v38, v38
	v_exp_f32_e32 v39, v39
	v_add_f32_e32 v234, v32, v34
	v_add_f32_e32 v235, v33, v35
	v_add_f32_e32 v234, v234, v36
	v_add_f32_e32 v235, v235, v37
	v_add_f32_e32 v234, v234, v38
	v_add_f32_e32 v235, v235, v39
	v_cvt_pk_bf16_f32 v32, v32, v33
	v_cvt_pk_bf16_f32 v33, v34, v35
	v_cvt_pk_bf16_f32 v34, v36, v37
	v_cvt_pk_bf16_f32 v35, v38, v39
	v_cmp_ge_i32_e64 s[2:3], 16, v178
	v_cmp_ge_i32_e64 s[4:5], 17, v178
	s_waitcnt lgkmcnt(14)
	v_mfma_f32_32x32x16_bf16 v[16:31], v[186:189], v[32:35], v[16:31]
	v_cmp_ge_i32_e64 s[24:25], 18, v178
	v_cmp_ge_i32_e64 s[26:27], 19, v178
	v_cndmask_b32_e64 v40, v238, v40, s[2:3]
	v_cndmask_b32_e64 v41, v238, v41, s[4:5]
	v_cndmask_b32_e64 v42, v238, v42, s[24:25]
	v_cndmask_b32_e64 v43, v238, v43, s[26:27]
	s_waitcnt lgkmcnt(12)
	v_mfma_f32_32x32x16_bf16 v[0:15], v[190:193], v[32:35], v[0:15]
	v_cmp_ge_i32_e64 s[2:3], 24, v178
	v_cmp_ge_i32_e64 s[4:5], 25, v178
	v_cmp_ge_i32_e64 s[24:25], 26, v178
	v_cmp_ge_i32_e64 s[26:27], 27, v178
	v_cndmask_b32_e64 v44, v238, v44, s[2:3]
	v_cndmask_b32_e64 v45, v238, v45, s[4:5]
	v_cndmask_b32_e64 v46, v238, v46, s[24:25]
	v_cndmask_b32_e64 v47, v238, v47, s[26:27]
	v_mul_f32_e32 v40, 0x3e38aa3b, v40
	v_mul_f32_e32 v41, 0x3e38aa3b, v41
	v_mul_f32_e32 v42, 0x3e38aa3b, v42
	v_mul_f32_e32 v43, 0x3e38aa3b, v43
	v_mul_f32_e32 v44, 0x3e38aa3b, v44
	v_mul_f32_e32 v45, 0x3e38aa3b, v45
	v_mul_f32_e32 v46, 0x3e38aa3b, v46
	v_mul_f32_e32 v47, 0x3e38aa3b, v47
	v_exp_f32_e32 v40, v40
	v_exp_f32_e32 v41, v41
	v_exp_f32_e32 v42, v42
	v_exp_f32_e32 v43, v43
	v_exp_f32_e32 v44, v44
	v_exp_f32_e32 v45, v45
	v_exp_f32_e32 v46, v46
	v_exp_f32_e32 v47, v47
	v_add_f32_e32 v234, v234, v40
	v_add_f32_e32 v235, v235, v41
	v_add_f32_e32 v234, v234, v42
	v_add_f32_e32 v235, v235, v43
	v_add_f32_e32 v234, v234, v44
	v_add_f32_e32 v235, v235, v45
	v_add_f32_e32 v234, v234, v46
	v_add_f32_e32 v235, v235, v47
	v_cvt_pk_bf16_f32 v40, v40, v41
	v_cvt_pk_bf16_f32 v41, v42, v43
	v_cvt_pk_bf16_f32 v42, v44, v45
	v_cvt_pk_bf16_f32 v43, v46, v47
	v_cmp_ge_i32_e64 s[2:3], 32, v178
	v_cmp_ge_i32_e64 s[4:5], 33, v178
	s_waitcnt lgkmcnt(10)
	v_mfma_f32_32x32x16_bf16 v[16:31], v[194:197], v[40:43], v[16:31]
	v_cmp_ge_i32_e64 s[24:25], 34, v178
	v_cmp_ge_i32_e64 s[26:27], 35, v178
	v_cndmask_b32_e64 v48, v238, v48, s[2:3]
	v_cndmask_b32_e64 v49, v238, v49, s[4:5]
	v_cndmask_b32_e64 v50, v238, v50, s[24:25]
	v_cndmask_b32_e64 v51, v238, v51, s[26:27]
	s_waitcnt lgkmcnt(8)
	v_mfma_f32_32x32x16_bf16 v[0:15], v[198:201], v[40:43], v[0:15]
	v_cmp_ge_i32_e64 s[2:3], 40, v178
	v_cmp_ge_i32_e64 s[4:5], 41, v178
	v_cmp_ge_i32_e64 s[24:25], 42, v178
	v_cmp_ge_i32_e64 s[26:27], 43, v178
	v_cndmask_b32_e64 v52, v238, v52, s[2:3]
	v_cndmask_b32_e64 v53, v238, v53, s[4:5]
	v_cndmask_b32_e64 v54, v238, v54, s[24:25]
	v_cndmask_b32_e64 v55, v238, v55, s[26:27]
	v_mul_f32_e32 v48, 0x3e38aa3b, v48
	v_mul_f32_e32 v49, 0x3e38aa3b, v49
	v_mul_f32_e32 v50, 0x3e38aa3b, v50
	v_mul_f32_e32 v51, 0x3e38aa3b, v51
	v_mul_f32_e32 v52, 0x3e38aa3b, v52
	v_mul_f32_e32 v53, 0x3e38aa3b, v53
	v_mul_f32_e32 v54, 0x3e38aa3b, v54
	v_mul_f32_e32 v55, 0x3e38aa3b, v55
	v_exp_f32_e32 v48, v48
	v_exp_f32_e32 v49, v49
	v_exp_f32_e32 v50, v50
	v_exp_f32_e32 v51, v51
	v_exp_f32_e32 v52, v52
	v_exp_f32_e32 v53, v53
	v_exp_f32_e32 v54, v54
	v_exp_f32_e32 v55, v55
	v_add_f32_e32 v234, v234, v48
	v_add_f32_e32 v235, v235, v49
	v_add_f32_e32 v234, v234, v50
	v_add_f32_e32 v235, v235, v51
	v_add_f32_e32 v234, v234, v52
	v_add_f32_e32 v235, v235, v53
	v_add_f32_e32 v234, v234, v54
	v_add_f32_e32 v235, v235, v55
	v_cvt_pk_bf16_f32 v48, v48, v49
	v_cvt_pk_bf16_f32 v49, v50, v51
	v_cvt_pk_bf16_f32 v50, v52, v53
	v_cvt_pk_bf16_f32 v51, v54, v55
	v_cmp_ge_i32_e64 s[2:3], 48, v178
	v_cmp_ge_i32_e64 s[4:5], 49, v178
	s_waitcnt lgkmcnt(6)
	v_mfma_f32_32x32x16_bf16 v[16:31], v[202:205], v[48:51], v[16:31]
	v_cmp_ge_i32_e64 s[24:25], 50, v178
	v_cmp_ge_i32_e64 s[26:27], 51, v178
	v_cndmask_b32_e64 v56, v238, v56, s[2:3]
	v_cndmask_b32_e64 v57, v238, v57, s[4:5]
	v_cndmask_b32_e64 v58, v238, v58, s[24:25]
	v_cndmask_b32_e64 v59, v238, v59, s[26:27]
	s_waitcnt lgkmcnt(4)
	v_mfma_f32_32x32x16_bf16 v[0:15], v[206:209], v[48:51], v[0:15]
	v_cmp_ge_i32_e64 s[2:3], 56, v178
	v_cmp_ge_i32_e64 s[4:5], 57, v178
	v_cmp_ge_i32_e64 s[24:25], 58, v178
	v_cmp_ge_i32_e64 s[26:27], 59, v178
	v_cndmask_b32_e64 v60, v238, v60, s[2:3]
	v_cndmask_b32_e64 v61, v238, v61, s[4:5]
	v_cndmask_b32_e64 v62, v238, v62, s[24:25]
	v_cndmask_b32_e64 v63, v238, v63, s[26:27]
	v_mul_f32_e32 v56, 0x3e38aa3b, v56
	v_mul_f32_e32 v57, 0x3e38aa3b, v57
	v_mul_f32_e32 v58, 0x3e38aa3b, v58
	v_mul_f32_e32 v59, 0x3e38aa3b, v59
	v_mul_f32_e32 v60, 0x3e38aa3b, v60
	v_mul_f32_e32 v61, 0x3e38aa3b, v61
	v_mul_f32_e32 v62, 0x3e38aa3b, v62
	v_mul_f32_e32 v63, 0x3e38aa3b, v63
	v_exp_f32_e32 v56, v56
	v_exp_f32_e32 v57, v57
	v_exp_f32_e32 v58, v58
	v_exp_f32_e32 v59, v59
	v_exp_f32_e32 v60, v60
	v_exp_f32_e32 v61, v61
	v_exp_f32_e32 v62, v62
	v_exp_f32_e32 v63, v63
	v_add_f32_e32 v234, v234, v56
	v_add_f32_e32 v235, v235, v57
	v_add_f32_e32 v234, v234, v58
	v_add_f32_e32 v235, v235, v59
	v_add_f32_e32 v234, v234, v60
	v_add_f32_e32 v235, v235, v61
	v_add_f32_e32 v234, v234, v62
	v_add_f32_e32 v235, v235, v63
	v_cvt_pk_bf16_f32 v56, v56, v57
	v_cvt_pk_bf16_f32 v57, v58, v59
	v_cvt_pk_bf16_f32 v58, v60, v61
	v_cvt_pk_bf16_f32 v59, v62, v63
	s_nop 1
	s_waitcnt lgkmcnt(2)
	v_mfma_f32_32x32x16_bf16 v[16:31], v[210:213], v[56:59], v[16:31]
	s_waitcnt lgkmcnt(0)
	v_mfma_f32_32x32x16_bf16 v[0:15], v[214:217], v[56:59], v[0:15]
	v_add_f32_e32 v234, v234, v235
	v_add_f32_e32 v163, v163, v234
	v_cmp_lt_f32_e32 vcc, 0x43000000, v234
	s_cbranch_vccz .Lm2_nr_lB
	s_nop 15
	v_mov_b32_e32 v235, v234
	s_nop 1
	v_permlane32_swap_b32_e32 v234, v235
	v_add_f32_e32 v178, v234, v235
	v_cmp_lt_f32_e32 vcc, 0x43800000, v178
	v_frexp_exp_i32_f32_e32 v179, v178
	s_nop 1
	v_cndmask_b32_e32 v179, 0, v179, vcc
	v_cvt_f32_i32_e32 v180, v179
	v_sub_u32_e32 v179, 0, v179
	v_ldexp_f32 v178, 1.0, v179
	v_add_f32_e32 v168, v168, v180
	v_mul_f32_e32 v163, v163, v178
	v_mul_f32_e32 v0, v0, v178
	v_mul_f32_e32 v1, v1, v178
	v_mul_f32_e32 v2, v2, v178
	v_mul_f32_e32 v3, v3, v178
	v_mul_f32_e32 v4, v4, v178
	v_mul_f32_e32 v5, v5, v178
	v_mul_f32_e32 v6, v6, v178
	v_mul_f32_e32 v7, v7, v178
	v_mul_f32_e32 v8, v8, v178
	v_mul_f32_e32 v9, v9, v178
	v_mul_f32_e32 v10, v10, v178
	v_mul_f32_e32 v11, v11, v178
	v_mul_f32_e32 v12, v12, v178
	v_mul_f32_e32 v13, v13, v178
	v_mul_f32_e32 v14, v14, v178
	v_mul_f32_e32 v15, v15, v178
	v_mul_f32_e32 v16, v16, v178
	v_mul_f32_e32 v17, v17, v178
	v_mul_f32_e32 v18, v18, v178
	v_mul_f32_e32 v19, v19, v178
	v_mul_f32_e32 v20, v20, v178
	v_mul_f32_e32 v21, v21, v178
	v_mul_f32_e32 v22, v22, v178
	v_mul_f32_e32 v23, v23, v178
	v_mul_f32_e32 v24, v24, v178
	v_mul_f32_e32 v25, v25, v178
	v_mul_f32_e32 v26, v26, v178
	v_mul_f32_e32 v27, v27, v178
	v_mul_f32_e32 v28, v28, v178
	v_mul_f32_e32 v29, v29, v178
	v_mul_f32_e32 v30, v30, v178
	v_mul_f32_e32 v31, v31, v178
	v_mul_f32_e32 v218, 0xc0b17218, v168
	v_mov_b32_e32 v219, v218
	v_mov_b32_e32 v220, v218
	v_mov_b32_e32 v221, v218
	v_mov_b32_e32 v222, v218
	v_mov_b32_e32 v223, v218
	v_mov_b32_e32 v224, v218
	v_mov_b32_e32 v225, v218
	v_mov_b32_e32 v226, v218
	v_mov_b32_e32 v227, v218
	v_mov_b32_e32 v228, v218
	v_mov_b32_e32 v229, v218
	v_mov_b32_e32 v230, v218
	v_mov_b32_e32 v231, v218
	v_mov_b32_e32 v232, v218
	v_mov_b32_e32 v233, v218

.Lm2_highB:
	v_add_u32_e32 v236, v174, v162
	ds_read_b128 v[128:131], v236 offset:13312
	ds_read_b128 v[144:147], v236 offset:19968
	ds_read_b128 v[132:135], v236 offset:13344
	ds_read_b128 v[148:151], v236 offset:20000
	ds_read_b128 v[136:139], v236 offset:13376
	ds_read_b128 v[152:155], v236 offset:20032
	ds_read_b128 v[140:143], v236 offset:13408
	ds_read_b128 v[156:159], v236 offset:20064
	v_add_u32_e32 v237, v176, v175
	s_sub_i32 s27, 0x80, s27
	v_sub_u32_e32 v178, s27, v177
	s_waitcnt lgkmcnt(7)
	v_mfma_f32_32x32x16_bf16 v[32:47], v[128:131], v[96:99], v[218:233]
	s_waitcnt lgkmcnt(6)
	v_mfma_f32_32x32x16_bf16 v[48:63], v[144:147], v[96:99], v[218:233]
	s_waitcnt lgkmcnt(5)
	v_mfma_f32_32x32x16_bf16 v[32:47], v[132:135], v[100:103], v[32:47]
	s_waitcnt lgkmcnt(4)
	v_mfma_f32_32x32x16_bf16 v[48:63], v[148:151], v[100:103], v[48:63]
	s_waitcnt lgkmcnt(3)
	v_mfma_f32_32x32x16_bf16 v[32:47], v[136:139], v[104:107], v[32:47]
	s_waitcnt lgkmcnt(2)
	v_mfma_f32_32x32x16_bf16 v[48:63], v[152:155], v[104:107], v[48:63]
	s_waitcnt lgkmcnt(1)
	v_mfma_f32_32x32x16_bf16 v[32:47], v[140:143], v[108:111], v[32:47]
	s_waitcnt lgkmcnt(0)
	v_mfma_f32_32x32x16_bf16 v[48:63], v[156:159], v[108:111], v[48:63]
	ds_read_b64_tr_b16 v[186:187], v237 offset:38912
	ds_read_b64_tr_b16 v[188:189], v237 offset:40448
	ds_read_b64_tr_b16 v[190:191], v237 offset:38976
	ds_read_b64_tr_b16 v[192:193], v237 offset:40512
	ds_read_b64_tr_b16 v[194:195], v237 offset:41984
	ds_read_b64_tr_b16 v[196:197], v237 offset:43520
	ds_read_b64_tr_b16 v[198:199], v237 offset:42048
	ds_read_b64_tr_b16 v[200:201], v237 offset:43584
	ds_read_b64_tr_b16 v[202:203], v237 offset:45056
	ds_read_b64_tr_b16 v[204:205], v237 offset:46592
	ds_read_b64_tr_b16 v[206:207], v237 offset:45120
	ds_read_b64_tr_b16 v[208:209], v237 offset:46656
	ds_read_b64_tr_b16 v[210:211], v237 offset:48128
	ds_read_b64_tr_b16 v[212:213], v237 offset:49664
	ds_read_b64_tr_b16 v[214:215], v237 offset:48192
	ds_read_b64_tr_b16 v[216:217], v237 offset:49728
	v_cmp_le_i32_e64 s[2:3], 0, v178
	v_cmp_le_i32_e64 s[4:5], 1, v178
	v_cmp_le_i32_e64 s[24:25], 2, v178
	v_cmp_le_i32_e64 s[26:27], 3, v178
	v_cndmask_b32_e64 v32, v238, v32, s[2:3]
	v_cndmask_b32_e64 v33, v238, v33, s[4:5]
	v_cndmask_b32_e64 v34, v238, v34, s[24:25]
	v_cndmask_b32_e64 v35, v238, v35, s[26:27]
	v_cmp_le_i32_e64 s[2:3], 8, v178
	v_cmp_le_i32_e64 s[4:5], 9, v178
	v_cmp_le_i32_e64 s[24:25], 10, v178
	v_cmp_le_i32_e64 s[26:27], 11, v178
	v_cndmask_b32_e64 v36, v238, v36, s[2:3]
	v_cndmask_b32_e64 v37, v238, v37, s[4:5]
	v_cndmask_b32_e64 v38, v238, v38, s[24:25]
	v_cndmask_b32_e64 v39, v238, v39, s[26:27]
	v_mul_f32_e32 v32, 0x3e38aa3b, v32
	v_mul_f32_e32 v33, 0x3e38aa3b, v33
	v_mul_f32_e32 v34, 0x3e38aa3b, v34
	v_mul_f32_e32 v35, 0x3e38aa3b, v35
	v_mul_f32_e32 v36, 0x3e38aa3b, v36
	v_mul_f32_e32 v37, 0x3e38aa3b, v37
	v_mul_f32_e32 v38, 0x3e38aa3b, v38
	v_mul_f32_e32 v39, 0x3e38aa3b, v39
	v_exp_f32_e32 v32, v32
	v_exp_f32_e32 v33, v33
	v_exp_f32_e32 v34, v34
	v_exp_f32_e32 v35, v35
	v_exp_f32_e32 v36, v36
	v_exp_f32_e32 v37, v37
	v_exp_f32_e32 v38, v38
	v_exp_f32_e32 v39, v39
	v_add_f32_e32 v234, v32, v34
	v_add_f32_e32 v235, v33, v35
	v_add_f32_e32 v234, v234, v36
	v_add_f32_e32 v235, v235, v37
	v_add_f32_e32 v234, v234, v38
	v_add_f32_e32 v235, v235, v39
	v_cvt_pk_bf16_f32 v32, v32, v33
	v_cvt_pk_bf16_f32 v33, v34, v35
	v_cvt_pk_bf16_f32 v34, v36, v37
	v_cvt_pk_bf16_f32 v35, v38, v39
	v_cmp_le_i32_e64 s[2:3], 16, v178
	v_cmp_le_i32_e64 s[4:5], 17, v178
	s_waitcnt lgkmcnt(14)
	v_mfma_f32_32x32x16_bf16 v[16:31], v[186:189], v[32:35], v[16:31]
	v_cmp_le_i32_e64 s[24:25], 18, v178
	v_cmp_le_i32_e64 s[26:27], 19, v178
	v_cndmask_b32_e64 v40, v238, v40, s[2:3]
	v_cndmask_b32_e64 v41, v238, v41, s[4:5]
	v_cndmask_b32_e64 v42, v238, v42, s[24:25]
	v_cndmask_b32_e64 v43, v238, v43, s[26:27]
	s_waitcnt lgkmcnt(12)
	v_mfma_f32_32x32x16_bf16 v[0:15], v[190:193], v[32:35], v[0:15]
	v_cmp_le_i32_e64 s[2:3], 24, v178
	v_cmp_le_i32_e64 s[4:5], 25, v178
	v_cmp_le_i32_e64 s[24:25], 26, v178
	v_cmp_le_i32_e64 s[26:27], 27, v178
	v_cndmask_b32_e64 v44, v238, v44, s[2:3]
	v_cndmask_b32_e64 v45, v238, v45, s[4:5]
	v_cndmask_b32_e64 v46, v238, v46, s[24:25]
	v_cndmask_b32_e64 v47, v238, v47, s[26:27]
	v_mul_f32_e32 v40, 0x3e38aa3b, v40
	v_mul_f32_e32 v41, 0x3e38aa3b, v41
	v_mul_f32_e32 v42, 0x3e38aa3b, v42
	v_mul_f32_e32 v43, 0x3e38aa3b, v43
	v_mul_f32_e32 v44, 0x3e38aa3b, v44
	v_mul_f32_e32 v45, 0x3e38aa3b, v45
	v_mul_f32_e32 v46, 0x3e38aa3b, v46
	v_mul_f32_e32 v47, 0x3e38aa3b, v47
	v_exp_f32_e32 v40, v40
	v_exp_f32_e32 v41, v41
	v_exp_f32_e32 v42, v42
	v_exp_f32_e32 v43, v43
	v_exp_f32_e32 v44, v44
	v_exp_f32_e32 v45, v45
	v_exp_f32_e32 v46, v46
	v_exp_f32_e32 v47, v47
	v_add_f32_e32 v234, v234, v40
	v_add_f32_e32 v235, v235, v41
	v_add_f32_e32 v234, v234, v42
	v_add_f32_e32 v235, v235, v43
	v_add_f32_e32 v234, v234, v44
	v_add_f32_e32 v235, v235, v45
	v_add_f32_e32 v234, v234, v46
	v_add_f32_e32 v235, v235, v47
	v_cvt_pk_bf16_f32 v40, v40, v41
	v_cvt_pk_bf16_f32 v41, v42, v43
	v_cvt_pk_bf16_f32 v42, v44, v45
	v_cvt_pk_bf16_f32 v43, v46, v47
	v_cmp_le_i32_e64 s[2:3], 32, v178
	v_cmp_le_i32_e64 s[4:5], 33, v178
	s_waitcnt lgkmcnt(10)
	v_mfma_f32_32x32x16_bf16 v[16:31], v[194:197], v[40:43], v[16:31]
	v_cmp_le_i32_e64 s[24:25], 34, v178
	v_cmp_le_i32_e64 s[26:27], 35, v178
	v_cndmask_b32_e64 v48, v238, v48, s[2:3]
	v_cndmask_b32_e64 v49, v238, v49, s[4:5]
	v_cndmask_b32_e64 v50, v238, v50, s[24:25]
	v_cndmask_b32_e64 v51, v238, v51, s[26:27]
	s_waitcnt lgkmcnt(8)
	v_mfma_f32_32x32x16_bf16 v[0:15], v[198:201], v[40:43], v[0:15]
	v_cmp_le_i32_e64 s[2:3], 40, v178
	v_cmp_le_i32_e64 s[4:5], 41, v178
	v_cmp_le_i32_e64 s[24:25], 42, v178
	v_cmp_le_i32_e64 s[26:27], 43, v178
	v_cndmask_b32_e64 v52, v238, v52, s[2:3]
	v_cndmask_b32_e64 v53, v238, v53, s[4:5]
	v_cndmask_b32_e64 v54, v238, v54, s[24:25]
	v_cndmask_b32_e64 v55, v238, v55, s[26:27]
	v_mul_f32_e32 v48, 0x3e38aa3b, v48
	v_mul_f32_e32 v49, 0x3e38aa3b, v49
	v_mul_f32_e32 v50, 0x3e38aa3b, v50
	v_mul_f32_e32 v51, 0x3e38aa3b, v51
	v_mul_f32_e32 v52, 0x3e38aa3b, v52
	v_mul_f32_e32 v53, 0x3e38aa3b, v53
	v_mul_f32_e32 v54, 0x3e38aa3b, v54
	v_mul_f32_e32 v55, 0x3e38aa3b, v55
	v_exp_f32_e32 v48, v48
	v_exp_f32_e32 v49, v49
	v_exp_f32_e32 v50, v50
	v_exp_f32_e32 v51, v51
	v_exp_f32_e32 v52, v52
	v_exp_f32_e32 v53, v53
	v_exp_f32_e32 v54, v54
	v_exp_f32_e32 v55, v55
	v_add_f32_e32 v234, v234, v48
	v_add_f32_e32 v235, v235, v49
	v_add_f32_e32 v234, v234, v50
	v_add_f32_e32 v235, v235, v51
	v_add_f32_e32 v234, v234, v52
	v_add_f32_e32 v235, v235, v53
	v_add_f32_e32 v234, v234, v54
	v_add_f32_e32 v235, v235, v55
	v_cvt_pk_bf16_f32 v48, v48, v49
	v_cvt_pk_bf16_f32 v49, v50, v51
	v_cvt_pk_bf16_f32 v50, v52, v53
	v_cvt_pk_bf16_f32 v51, v54, v55
	v_cmp_le_i32_e64 s[2:3], 48, v178
	v_cmp_le_i32_e64 s[4:5], 49, v178
	s_waitcnt lgkmcnt(6)
	v_mfma_f32_32x32x16_bf16 v[16:31], v[202:205], v[48:51], v[16:31]
	v_cmp_le_i32_e64 s[24:25], 50, v178
	v_cmp_le_i32_e64 s[26:27], 51, v178
	v_cndmask_b32_e64 v56, v238, v56, s[2:3]
	v_cndmask_b32_e64 v57, v238, v57, s[4:5]
	v_cndmask_b32_e64 v58, v238, v58, s[24:25]
	v_cndmask_b32_e64 v59, v238, v59, s[26:27]
	s_waitcnt lgkmcnt(4)
	v_mfma_f32_32x32x16_bf16 v[0:15], v[206:209], v[48:51], v[0:15]
	v_cmp_le_i32_e64 s[2:3], 56, v178
	v_cmp_le_i32_e64 s[4:5], 57, v178
	v_cmp_le_i32_e64 s[24:25], 58, v178
	v_cmp_le_i32_e64 s[26:27], 59, v178
	v_cndmask_b32_e64 v60, v238, v60, s[2:3]
	v_cndmask_b32_e64 v61, v238, v61, s[4:5]
	v_cndmask_b32_e64 v62, v238, v62, s[24:25]
	v_cndmask_b32_e64 v63, v238, v63, s[26:27]
	v_mul_f32_e32 v56, 0x3e38aa3b, v56
	v_mul_f32_e32 v57, 0x3e38aa3b, v57
	v_mul_f32_e32 v58, 0x3e38aa3b, v58
	v_mul_f32_e32 v59, 0x3e38aa3b, v59
	v_mul_f32_e32 v60, 0x3e38aa3b, v60
	v_mul_f32_e32 v61, 0x3e38aa3b, v61
	v_mul_f32_e32 v62, 0x3e38aa3b, v62
	v_mul_f32_e32 v63, 0x3e38aa3b, v63
	v_exp_f32_e32 v56, v56
	v_exp_f32_e32 v57, v57
	v_exp_f32_e32 v58, v58
	v_exp_f32_e32 v59, v59
	v_exp_f32_e32 v60, v60
	v_exp_f32_e32 v61, v61
	v_exp_f32_e32 v62, v62
	v_exp_f32_e32 v63, v63
	v_add_f32_e32 v234, v234, v56
	v_add_f32_e32 v235, v235, v57
	v_add_f32_e32 v234, v234, v58
	v_add_f32_e32 v235, v235, v59
	v_add_f32_e32 v234, v234, v60
	v_add_f32_e32 v235, v235, v61
	v_add_f32_e32 v234, v234, v62
	v_add_f32_e32 v235, v235, v63
	v_cvt_pk_bf16_f32 v56, v56, v57
	v_cvt_pk_bf16_f32 v57, v58, v59
	v_cvt_pk_bf16_f32 v58, v60, v61
	v_cvt_pk_bf16_f32 v59, v62, v63
	s_nop 1
	s_waitcnt lgkmcnt(2)
	v_mfma_f32_32x32x16_bf16 v[16:31], v[210:213], v[56:59], v[16:31]
	s_waitcnt lgkmcnt(0)
	v_mfma_f32_32x32x16_bf16 v[0:15], v[214:217], v[56:59], v[0:15]
	v_add_f32_e32 v234, v234, v235
	v_add_f32_e32 v163, v163, v234
	v_cmp_lt_f32_e32 vcc, 0x43000000, v234
	s_cbranch_vccz .Lm2_nr_hB
	s_nop 15
	v_mov_b32_e32 v235, v234
	s_nop 1
	v_permlane32_swap_b32_e32 v234, v235
	v_add_f32_e32 v178, v234, v235
	v_cmp_lt_f32_e32 vcc, 0x43800000, v178
	v_frexp_exp_i32_f32_e32 v179, v178
	s_nop 1
	v_cndmask_b32_e32 v179, 0, v179, vcc
	v_cvt_f32_i32_e32 v180, v179
	v_sub_u32_e32 v179, 0, v179
	v_ldexp_f32 v178, 1.0, v179
	v_add_f32_e32 v168, v168, v180
	v_mul_f32_e32 v163, v163, v178
	v_mul_f32_e32 v0, v0, v178
	v_mul_f32_e32 v1, v1, v178
	v_mul_f32_e32 v2, v2, v178
	v_mul_f32_e32 v3, v3, v178
	v_mul_f32_e32 v4, v4, v178
	v_mul_f32_e32 v5, v5, v178
	v_mul_f32_e32 v6, v6, v178
	v_mul_f32_e32 v7, v7, v178
	v_mul_f32_e32 v8, v8, v178
	v_mul_f32_e32 v9, v9, v178
	v_mul_f32_e32 v10, v10, v178
	v_mul_f32_e32 v11, v11, v178
	v_mul_f32_e32 v12, v12, v178
	v_mul_f32_e32 v13, v13, v178
	v_mul_f32_e32 v14, v14, v178
	v_mul_f32_e32 v15, v15, v178
	v_mul_f32_e32 v16, v16, v178
	v_mul_f32_e32 v17, v17, v178
	v_mul_f32_e32 v18, v18, v178
	v_mul_f32_e32 v19, v19, v178
	v_mul_f32_e32 v20, v20, v178
	v_mul_f32_e32 v21, v21, v178
	v_mul_f32_e32 v22, v22, v178
	v_mul_f32_e32 v23, v23, v178
	v_mul_f32_e32 v24, v24, v178
	v_mul_f32_e32 v25, v25, v178
	v_mul_f32_e32 v26, v26, v178
	v_mul_f32_e32 v27, v27, v178
	v_mul_f32_e32 v28, v28, v178
	v_mul_f32_e32 v29, v29, v178
	v_mul_f32_e32 v30, v30, v178
	v_mul_f32_e32 v31, v31, v178
	v_mul_f32_e32 v218, 0xc0b17218, v168
	v_mov_b32_e32 v219, v218
	v_mov_b32_e32 v220, v218
	v_mov_b32_e32 v221, v218
	v_mov_b32_e32 v222, v218
	v_mov_b32_e32 v223, v218
	v_mov_b32_e32 v224, v218
	v_mov_b32_e32 v225, v218
	v_mov_b32_e32 v226, v218
	v_mov_b32_e32 v227, v218
	v_mov_b32_e32 v228, v218
	v_mov_b32_e32 v229, v218
	v_mov_b32_e32 v230, v218
	v_mov_b32_e32 v231, v218
	v_mov_b32_e32 v232, v218
	v_mov_b32_e32 v233, v218
.Lm2_nr_hB:
.Lm2_doneB:
	s_add_i32 s24, s19, -1
	s_cmp_ge_i32 s24, s6
	s_cbranch_scc1 .Lm2_nwB
	s_waitcnt vmcnt(3)
	ds_write_b128 v172, v[120:123]
	s_waitcnt vmcnt(2)
	ds_write_b128 v173, v[124:127] offset:26624
.Lm2_nwB:
	s_waitcnt lgkmcnt(0)
	s_barrier
	s_addk_i32 s21, 0x80
	s_add_i32 s19, s19, 2
	s_add_i32 s24, s19, -3
	s_cmp_ge_i32 s24, s6
	s_cbranch_scc0 .LBB0_1072
	s_branch .LBB0_1060
